# cache policy for read-once data: nt hint on the residual-tile loads of the three residual-add epilogues
# baseline (speedup 1.0000x reference)
;     __device__ __forceinline__ void operator()(const f32x4 (&acc)[2][2][4][2], const pg8::Unit& u, int wr, int wc, int fr_, int fq_, int tid) {
;     ...
;         const size_t base = (size_t)row0 * DM + col0;
;         f32x4 cur[4], nxt[4];
;     ...
;         ER_LD(cur, 0);
; #pragma unroll
;         for (int g = 0; g < 8; ++g) {
;             const int ai = g >> 2, m = g & 3;
;             if (g < 7) ER_LD(nxt, g + 1);
.LBB0_251:
	s_lshl_b32 s6, s52, 8
	v_mov_b32_e32 v218, v173
	v_mov_b32_e32 v130, v1
	s_add_i32 s6, s6, s42
	s_andn2_b64 vcc, exec, s[18:19]
	v_add_u32_e32 v188, s6, v130
	s_lshl_b32 s6, s51, 8
	s_or_b32 s6, s6, s43
	v_lshl_add_u32 v130, v218, 3, s6
	v_ashrrev_i32_e32 v189, 31, v188
	v_lshlrev_b64 v[132:133], 11, v[188:189]
	v_ashrrev_i32_e32 v131, 31, v130
	v_lshl_add_u64 v[130:131], v[132:133], 0, v[130:131]
	v_cndmask_b32_e64 v132, 0, 1, s[18:19]
	v_cmp_ne_u32_e64 s[8:9], 1, v132
	v_lshl_add_u64 v[186:187], v[130:131], 2, s[10:11]
	s_cbranch_vccnz .LBB0_294
	global_load_dwordx4 v[154:157], v[186:187], off offset:16 nt
	global_load_dwordx4 v[158:161], v[186:187], off nt
	global_load_dwordx4 v[146:149], v[186:187], off offset:528 nt
	global_load_dwordx4 v[150:153], v[186:187], off offset:512 nt
	v_lshl_add_u64 v[184:185], v[130:131], 1, s[12:13]
	s_cbranch_execnz .LBB0_254
.LBB0_253:
	global_load_dwordx4 v[132:135], v[184:185], off nt
	global_load_dwordx4 v[136:139], v[184:185], off offset:256 nt
	s_waitcnt vmcnt(0)
	v_lshlrev_b32_e32 v158, 16, v132
	v_and_b32_e32 v159, 0xffff0000, v132
	v_lshlrev_b32_e32 v160, 16, v133
	v_and_b32_e32 v161, 0xffff0000, v133
	v_lshlrev_b32_e32 v154, 16, v134
	v_and_b32_e32 v155, 0xffff0000, v134
	v_lshlrev_b32_e32 v156, 16, v135
	v_and_b32_e32 v157, 0xffff0000, v135
	v_lshlrev_b32_e32 v150, 16, v136
	v_and_b32_e32 v151, 0xffff0000, v136
	v_lshlrev_b32_e32 v152, 16, v137
	v_and_b32_e32 v153, 0xffff0000, v137
	v_lshlrev_b32_e32 v146, 16, v138
	v_and_b32_e32 v147, 0xffff0000, v138
	v_lshlrev_b32_e32 v148, 16, v139
	v_and_b32_e32 v149, 0xffff0000, v139
.LBB0_254:
	s_mov_b64 s[6:7], 0x8000
	s_and_b64 vcc, exec, s[8:9]
	v_lshl_add_u64 v[190:191], v[130:131], 0, s[6:7]
	s_cbranch_vccnz .LBB0_295
	v_lshl_add_u64 v[130:131], v[190:191], 2, s[10:11]
	global_load_dwordx4 v[142:145], v[130:131], off nt
	global_load_dwordx4 v[138:141], v[130:131], off offset:16 nt
	global_load_dwordx4 v[134:137], v[130:131], off offset:512 nt
	s_nop 0
	global_load_dwordx4 v[130:133], v[130:131], off offset:528 nt
	s_cbranch_execnz .LBB0_257
.LBB0_256:
	s_waitcnt vmcnt(0)
	v_lshl_add_u64 v[134:135], v[190:191], 1, s[12:13]
	global_load_dwordx4 v[130:133], v[134:135], off nt
	global_load_dwordx4 v[220:223], v[134:135], off offset:256 nt
	s_waitcnt vmcnt(1)
	v_lshlrev_b32_e32 v142, 16, v130
	v_and_b32_e32 v143, 0xffff0000, v130
	v_lshlrev_b32_e32 v144, 16, v131
	v_and_b32_e32 v145, 0xffff0000, v131
	v_lshlrev_b32_e32 v138, 16, v132
	v_and_b32_e32 v139, 0xffff0000, v132
	v_lshlrev_b32_e32 v140, 16, v133
	v_and_b32_e32 v141, 0xffff0000, v133
	s_waitcnt vmcnt(0)
	v_lshlrev_b32_e32 v134, 16, v220
	v_and_b32_e32 v135, 0xffff0000, v220
	v_lshlrev_b32_e32 v136, 16, v221
	v_and_b32_e32 v137, 0xffff0000, v221
	v_lshlrev_b32_e32 v130, 16, v222
	v_and_b32_e32 v131, 0xffff0000, v222
	v_lshlrev_b32_e32 v132, 16, v223
	v_and_b32_e32 v133, 0xffff0000, v223

;     __device__ __forceinline__ void operator()(const f32x4 (&acc)[2][2][4][2], const pg8::Unit& u, int wr, int wc, int fr_, int fq_, int tid) {
;     ...
;             if (g < 7) ER_LD(nxt, g + 1);
.LBB0_259:
	s_or_b64 exec, exec, s[26:27]
	s_and_b64 vcc, exec, s[8:9]
	s_cbranch_vccnz .LBB0_296
	s_mov_b64 s[26:27], 0x40000
	v_add_co_u32_e32 v116, vcc, 0x40000, v186
	s_waitcnt lgkmcnt(0)
	v_lshl_add_u64 v[114:115], v[186:187], 0, s[26:27]
	v_addc_co_u32_e32 v117, vcc, 0, v187, vcc
	global_load_dwordx4 v[122:125], v[114:115], off offset:16 nt
	global_load_dwordx4 v[118:121], v[114:115], off offset:512 nt
	global_load_dwordx4 v[126:129], v[116:117], off nt
	s_nop 0
	global_load_dwordx4 v[114:117], v[114:115], off offset:528 nt
	s_cbranch_execnz .LBB0_262
.LBB0_261:
	s_waitcnt vmcnt(0)
	v_add_co_u32_e32 v114, vcc, 0x20000, v184
	v_lshl_add_u64 v[118:119], v[184:185], 0, s[64:65]
	s_waitcnt lgkmcnt(0)
	v_addc_co_u32_e32 v115, vcc, 0, v185, vcc
	global_load_dwordx4 v[114:117], v[114:115], off nt
	s_nop 0
	global_load_dwordx4 v[150:153], v[118:119], off offset:256 nt
	s_waitcnt vmcnt(1)
	v_lshlrev_b32_e32 v126, 16, v114
	v_and_b32_e32 v127, 0xffff0000, v114
	v_lshlrev_b32_e32 v128, 16, v115
	v_and_b32_e32 v129, 0xffff0000, v115
	v_lshlrev_b32_e32 v122, 16, v116
	v_and_b32_e32 v123, 0xffff0000, v116
	v_lshlrev_b32_e32 v124, 16, v117
	v_and_b32_e32 v125, 0xffff0000, v117
	s_waitcnt vmcnt(0)
	v_lshlrev_b32_e32 v118, 16, v150
	v_and_b32_e32 v119, 0xffff0000, v150
	v_lshlrev_b32_e32 v120, 16, v151
	v_and_b32_e32 v121, 0xffff0000, v151
	v_lshlrev_b32_e32 v114, 16, v152
	v_and_b32_e32 v115, 0xffff0000, v152
	v_lshlrev_b32_e32 v116, 16, v153
	v_and_b32_e32 v117, 0xffff0000, v153

;     __device__ __forceinline__ void operator()(const f32x4 (&acc)[2][2][4][2], const pg8::Unit& u, int wr, int wc, int fr_, int fq_, int tid) {
;     ...
;             if (g < 7) ER_LD(nxt, g + 1);
.LBB0_264:
	s_or_b64 exec, exec, s[26:27]
	s_and_b64 vcc, exec, s[8:9]
	s_cbranch_vccnz .LBB0_297
	s_mov_b64 s[26:27], 0x60000
	v_add_co_u32_e32 v100, vcc, 0x60000, v186
	s_waitcnt lgkmcnt(0)
	v_lshl_add_u64 v[98:99], v[186:187], 0, s[26:27]
	v_addc_co_u32_e32 v101, vcc, 0, v187, vcc
	global_load_dwordx4 v[106:109], v[98:99], off offset:16 nt
	global_load_dwordx4 v[102:105], v[98:99], off offset:512 nt
	global_load_dwordx4 v[110:113], v[100:101], off nt
	s_nop 0
	global_load_dwordx4 v[98:101], v[98:99], off offset:528 nt
	s_cbranch_execnz .LBB0_267
.LBB0_266:
	s_waitcnt vmcnt(0)
	v_add_co_u32_e32 v98, vcc, 0x30000, v184
	v_lshl_add_u64 v[102:103], v[184:185], 0, s[66:67]
	s_waitcnt lgkmcnt(0)
	v_addc_co_u32_e32 v99, vcc, 0, v185, vcc
	global_load_dwordx4 v[98:101], v[98:99], off nt
	s_nop 0
	global_load_dwordx4 v[130:133], v[102:103], off offset:256 nt
	s_waitcnt vmcnt(1)
	v_lshlrev_b32_e32 v110, 16, v98
	v_and_b32_e32 v111, 0xffff0000, v98
	v_lshlrev_b32_e32 v112, 16, v99
	v_and_b32_e32 v113, 0xffff0000, v99
	v_lshlrev_b32_e32 v106, 16, v100
	v_and_b32_e32 v107, 0xffff0000, v100
	v_lshlrev_b32_e32 v108, 16, v101
	v_and_b32_e32 v109, 0xffff0000, v101
	s_waitcnt vmcnt(0)
	v_lshlrev_b32_e32 v102, 16, v130
	v_and_b32_e32 v103, 0xffff0000, v130
	v_lshlrev_b32_e32 v104, 16, v131
	v_and_b32_e32 v105, 0xffff0000, v131
	v_lshlrev_b32_e32 v98, 16, v132
	v_and_b32_e32 v99, 0xffff0000, v132
	v_lshlrev_b32_e32 v100, 16, v133
	v_and_b32_e32 v101, 0xffff0000, v133

;     __device__ __forceinline__ void operator()(const f32x4 (&acc)[2][2][4][2], const pg8::Unit& u, int wr, int wc, int fr_, int fq_, int tid) {
;     ...
;             if (g < 7) ER_LD(nxt, g + 1);
.LBB0_269:
	s_or_b64 exec, exec, s[26:27]
	s_and_b64 vcc, exec, s[8:9]
	s_cbranch_vccnz .LBB0_298
	s_mov_b64 s[26:27], 0x100000
	v_add_co_u32_e32 v84, vcc, 0x100000, v186
	s_waitcnt lgkmcnt(0)
	v_lshl_add_u64 v[82:83], v[186:187], 0, s[26:27]
	v_addc_co_u32_e32 v85, vcc, 0, v187, vcc
	global_load_dwordx4 v[90:93], v[82:83], off offset:16 nt
	global_load_dwordx4 v[86:89], v[82:83], off offset:512 nt
	global_load_dwordx4 v[94:97], v[84:85], off nt
	s_nop 0
	global_load_dwordx4 v[82:85], v[82:83], off offset:528 nt
	s_cbranch_execnz .LBB0_272
.LBB0_271:
	s_waitcnt vmcnt(0)
	v_add_co_u32_e32 v82, vcc, 0x80000, v184
	v_lshl_add_u64 v[86:87], v[184:185], 0, s[94:95]
	s_waitcnt lgkmcnt(0)
	v_addc_co_u32_e32 v83, vcc, 0, v185, vcc
	global_load_dwordx4 v[82:85], v[82:83], off nt
	s_nop 0
	global_load_dwordx4 v[114:117], v[86:87], off offset:256 nt
	s_waitcnt vmcnt(1)
	v_lshlrev_b32_e32 v94, 16, v82
	v_and_b32_e32 v95, 0xffff0000, v82
	v_lshlrev_b32_e32 v96, 16, v83
	v_and_b32_e32 v97, 0xffff0000, v83
	v_lshlrev_b32_e32 v90, 16, v84
	v_and_b32_e32 v91, 0xffff0000, v84
	v_lshlrev_b32_e32 v92, 16, v85
	v_and_b32_e32 v93, 0xffff0000, v85
	s_waitcnt vmcnt(0)
	v_lshlrev_b32_e32 v86, 16, v114
	v_and_b32_e32 v87, 0xffff0000, v114
	v_lshlrev_b32_e32 v88, 16, v115
	v_and_b32_e32 v89, 0xffff0000, v115
	v_lshlrev_b32_e32 v82, 16, v116
	v_and_b32_e32 v83, 0xffff0000, v116
	v_lshlrev_b32_e32 v84, 16, v117
	v_and_b32_e32 v85, 0xffff0000, v117

;     __device__ __forceinline__ void operator()(const f32x4 (&acc)[2][2][4][2], const pg8::Unit& u, int wr, int wc, int fr_, int fq_, int tid) {
;     ...
;             if (g < 7) ER_LD(nxt, g + 1);
.LBB0_274:
	s_or_b64 exec, exec, s[26:27]
	s_and_b64 vcc, exec, s[8:9]
	s_cbranch_vccnz .LBB0_299
	s_mov_b64 s[26:27], 0x120000
	v_add_co_u32_e32 v68, vcc, 0x120000, v186
	s_waitcnt lgkmcnt(0)
	v_lshl_add_u64 v[66:67], v[186:187], 0, s[26:27]
	v_addc_co_u32_e32 v69, vcc, 0, v187, vcc
	global_load_dwordx4 v[74:77], v[66:67], off offset:16 nt
	global_load_dwordx4 v[70:73], v[66:67], off offset:512 nt
	global_load_dwordx4 v[78:81], v[68:69], off nt
	s_nop 0
	global_load_dwordx4 v[66:69], v[66:67], off offset:528 nt
	s_cbranch_execnz .LBB0_277
.LBB0_276:
	s_waitcnt vmcnt(0)
	v_add_co_u32_e32 v66, vcc, 0x90000, v184
	v_lshl_add_u64 v[70:71], v[184:185], 0, s[68:69]
	s_waitcnt lgkmcnt(0)
	v_addc_co_u32_e32 v67, vcc, 0, v185, vcc
	global_load_dwordx4 v[66:69], v[66:67], off nt
	s_nop 0
	global_load_dwordx4 v[98:101], v[70:71], off offset:256 nt
	s_waitcnt vmcnt(1)
	v_lshlrev_b32_e32 v78, 16, v66
	v_and_b32_e32 v79, 0xffff0000, v66
	v_lshlrev_b32_e32 v80, 16, v67
	v_and_b32_e32 v81, 0xffff0000, v67
	v_lshlrev_b32_e32 v74, 16, v68
	v_and_b32_e32 v75, 0xffff0000, v68
	v_lshlrev_b32_e32 v76, 16, v69
	v_and_b32_e32 v77, 0xffff0000, v69
	s_waitcnt vmcnt(0)
	v_lshlrev_b32_e32 v70, 16, v98
	v_and_b32_e32 v71, 0xffff0000, v98
	v_lshlrev_b32_e32 v72, 16, v99
	v_and_b32_e32 v73, 0xffff0000, v99
	v_lshlrev_b32_e32 v66, 16, v100
	v_and_b32_e32 v67, 0xffff0000, v100
	v_lshlrev_b32_e32 v68, 16, v101
	v_and_b32_e32 v69, 0xffff0000, v101

;     __device__ __forceinline__ void operator()(const f32x4 (&acc)[2][2][4][2], const pg8::Unit& u, int wr, int wc, int fr_, int fq_, int tid) {
;     ...
;             if (g < 7) ER_LD(nxt, g + 1);
.LBB0_279:
	s_or_b64 exec, exec, s[26:27]
	s_and_b64 vcc, exec, s[8:9]
	s_cbranch_vccnz .LBB0_300
	s_mov_b64 s[26:27], 0x140000
	v_add_co_u32_e32 v52, vcc, 0x140000, v186
	s_waitcnt lgkmcnt(0)
	v_lshl_add_u64 v[50:51], v[186:187], 0, s[26:27]
	v_addc_co_u32_e32 v53, vcc, 0, v187, vcc
	global_load_dwordx4 v[58:61], v[50:51], off offset:16 nt
	global_load_dwordx4 v[54:57], v[50:51], off offset:512 nt
	global_load_dwordx4 v[62:65], v[52:53], off nt
	s_nop 0
	global_load_dwordx4 v[50:53], v[50:51], off offset:528 nt
	s_cbranch_execnz .LBB0_282
.LBB0_281:
	s_waitcnt vmcnt(0)
	v_add_co_u32_e32 v50, vcc, 0xa0000, v184
	v_lshl_add_u64 v[54:55], v[184:185], 0, s[70:71]
	s_waitcnt lgkmcnt(0)
	v_addc_co_u32_e32 v51, vcc, 0, v185, vcc
	global_load_dwordx4 v[50:53], v[50:51], off nt
	s_nop 0
	global_load_dwordx4 v[82:85], v[54:55], off offset:256 nt
	s_waitcnt vmcnt(1)
	v_lshlrev_b32_e32 v62, 16, v50
	v_and_b32_e32 v63, 0xffff0000, v50
	v_lshlrev_b32_e32 v64, 16, v51
	v_and_b32_e32 v65, 0xffff0000, v51
	v_lshlrev_b32_e32 v58, 16, v52
	v_and_b32_e32 v59, 0xffff0000, v52
	v_lshlrev_b32_e32 v60, 16, v53
	v_and_b32_e32 v61, 0xffff0000, v53
	s_waitcnt vmcnt(0)
	v_lshlrev_b32_e32 v54, 16, v82
	v_and_b32_e32 v55, 0xffff0000, v82
	v_lshlrev_b32_e32 v56, 16, v83
	v_and_b32_e32 v57, 0xffff0000, v83
	v_lshlrev_b32_e32 v50, 16, v84
	v_and_b32_e32 v51, 0xffff0000, v84
	v_lshlrev_b32_e32 v52, 16, v85
	v_and_b32_e32 v53, 0xffff0000, v85

;     __device__ __forceinline__ void operator()(const f32x4 (&acc)[2][2][4][2], const pg8::Unit& u, int wr, int wc, int fr_, int fq_, int tid) {
;     ...
;             if (g < 7) ER_LD(nxt, g + 1);
.LBB0_284:
	s_or_b64 exec, exec, s[26:27]
	s_and_b64 vcc, exec, s[8:9]
	s_cbranch_vccnz .LBB0_301
	s_mov_b64 s[8:9], 0x160000
	v_add_co_u32_e32 v36, vcc, 0x160000, v186
	s_waitcnt lgkmcnt(0)
	v_lshl_add_u64 v[34:35], v[186:187], 0, s[8:9]
	v_addc_co_u32_e32 v37, vcc, 0, v187, vcc
	global_load_dwordx4 v[42:45], v[34:35], off offset:16 nt
	global_load_dwordx4 v[38:41], v[34:35], off offset:512 nt
	global_load_dwordx4 v[46:49], v[36:37], off nt
	s_nop 0
	global_load_dwordx4 v[34:37], v[34:35], off offset:528 nt
	s_cbranch_execnz .LBB0_287
.LBB0_286:
	s_waitcnt vmcnt(0)
	v_add_co_u32_e32 v34, vcc, 0xb0000, v184
	v_lshl_add_u64 v[38:39], v[184:185], 0, s[72:73]
	s_waitcnt lgkmcnt(0)
	v_addc_co_u32_e32 v35, vcc, 0, v185, vcc
	global_load_dwordx4 v[34:37], v[34:35], off nt
	s_nop 0
	global_load_dwordx4 v[66:69], v[38:39], off offset:256 nt
	s_waitcnt vmcnt(1)
	v_lshlrev_b32_e32 v46, 16, v34
	v_and_b32_e32 v47, 0xffff0000, v34
	v_lshlrev_b32_e32 v48, 16, v35
	v_and_b32_e32 v49, 0xffff0000, v35
	v_lshlrev_b32_e32 v42, 16, v36
	v_and_b32_e32 v43, 0xffff0000, v36
	v_lshlrev_b32_e32 v44, 16, v37
	v_and_b32_e32 v45, 0xffff0000, v37
	s_waitcnt vmcnt(0)
	v_lshlrev_b32_e32 v38, 16, v66
	v_and_b32_e32 v39, 0xffff0000, v66
	v_lshlrev_b32_e32 v40, 16, v67
	v_and_b32_e32 v41, 0xffff0000, v67
	v_lshlrev_b32_e32 v34, 16, v68
	v_and_b32_e32 v35, 0xffff0000, v68
	v_lshlrev_b32_e32 v36, 16, v69
	v_and_b32_e32 v37, 0xffff0000, v69

;     __device__ __forceinline__ void operator()(const f32x4 (&acc)[2][2][4][2], const pg8::Unit& u, int wr, int wc, int fr_, int fq_, int tid) {
;     ...
;         const size_t base = (size_t)row0 * DM + col0;
;         f32x4 cur[4], nxt[4];
;     ...
;         ER_LD(cur, 0);
; #pragma unroll
;         for (int g = 0; g < 8; ++g) {
;             const int ai = g >> 2, m = g & 3;
;             if (g < 7) ER_LD(nxt, g + 1);
;             const size_t off = base + (size_t)(ai * 128 + m * 16) * DM; float s = 0.f;
; #pragma unroll
;             for (int bj = 0; bj < 2; ++bj) {
;                 const f32x4 n0 = cur[2 * bj] + acc[ai][bj][m][0] * alpha, n1 = cur[2 * bj + 1] + acc[ai][bj][m][1] * alpha;
;                 const u32x4 w = pack8bf(n0, n1);
;                 *(u32x4*)(xb + off + bj * 128) = w;
;                 float q[8]; unpack8(w, q);
;                 s += ((q[0] * q[0] + q[1] * q[1]) + (q[2] * q[2] + q[3] * q[3])) + ((q[4] * q[4] + q[5] * q[5]) + (q[6] * q[6] + q[7] * q[7]));
;             }
;             s += __shfl_xor(s, 16); s += __shfl_xor(s, 32);
;             if (fq == 0) ssq[(size_t)(row0 + ai * 128 + m * 16) * 32 + u.pn * 4 + wc] = s;
.LBB0_1027:
	s_lshl_b32 s7, s22, 8
	v_mov_b32_e32 v130, v1
	v_mov_b32_e32 v173, v150
	s_add_i32 s7, s7, s44
	v_cmp_lt_i32_e32 vcc, v203, v198
	v_add_u32_e32 v174, s7, v130
	s_lshl_b32 s7, s6, 8
	s_or_b32 s7, s7, s45
	v_ashrrev_i32_e32 v175, 31, v174
	v_lshl_add_u32 v130, v173, 3, s7
	v_lshlrev_b64 v[132:133], 12, v[174:175]
	v_ashrrev_i32_e32 v131, 31, v130
	v_lshl_add_u64 v[132:133], s[8:9], 0, v[132:133]
	v_lshl_add_u64 v[148:149], v[130:131], 1, v[132:133]
	global_load_dwordx4 v[154:157], v[148:149], off nt
	global_load_dwordx4 v[158:161], v[148:149], off offset:256 nt
	v_cndmask_b32_e32 v130, v195, v203, vcc
	v_lshlrev_b32_e32 v153, 2, v130
	v_add_co_u32_e32 v130, vcc, s86, v148
	s_lshl_b32 s22, s6, 2
	s_nop 0
	v_addc_co_u32_e32 v131, vcc, 0, v149, vcc
	global_load_dwordx4 v[134:137], v[130:131], off nt
	s_nop 0
	global_load_dwordx4 v[130:133], v[130:131], off offset:256 nt
	v_cmp_lt_i32_e32 vcc, v204, v198
	v_cmp_eq_u32_e64 s[6:7], 0, v173
	s_ashr_i32 s23, s22, 31
	s_waitcnt vmcnt(0)
	v_lshlrev_b32_e32 v176, 16, v154
	v_and_b32_e32 v177, 0xffff0000, v154
	v_lshlrev_b32_e32 v154, 16, v155
	v_and_b32_e32 v155, 0xffff0000, v155
	v_lshlrev_b32_e32 v178, 16, v156
	v_and_b32_e32 v179, 0xffff0000, v156
	v_lshlrev_b32_e32 v156, 16, v157
	v_and_b32_e32 v157, 0xffff0000, v157
	v_lshlrev_b32_e32 v182, 16, v160
	v_and_b32_e32 v183, 0xffff0000, v160
	v_lshlrev_b32_e32 v180, 16, v158
	v_and_b32_e32 v181, 0xffff0000, v158
	v_lshlrev_b32_e32 v158, 16, v159
	v_and_b32_e32 v159, 0xffff0000, v159
	v_lshlrev_b32_e32 v160, 16, v161
	v_and_b32_e32 v161, 0xffff0000, v161
	v_pk_add_f32 v[128:129], v[128:129], v[154:155]
	v_pk_add_f32 v[126:127], v[126:127], v[176:177]
	v_pk_add_f32 v[124:125], v[124:125], v[156:157]
	v_pk_add_f32 v[122:123], v[122:123], v[178:179]
	v_pk_add_f32 v[156:157], v[114:115], v[182:183]
	v_cvt_pk_bf16_f32 v114, v126, v127
	v_cvt_pk_bf16_f32 v115, v128, v129
	v_pk_add_f32 v[120:121], v[120:121], v[158:159]
	v_pk_add_f32 v[118:119], v[118:119], v[180:181]
	v_pk_add_f32 v[154:155], v[116:117], v[160:161]
	v_cvt_pk_bf16_f32 v116, v122, v123
	v_cvt_pk_bf16_f32 v117, v124, v125
	global_store_dwordx4 v[148:149], v[114:117], off
	v_lshlrev_b32_e32 v122, 16, v114
	v_lshlrev_b32_e32 v123, 16, v115
	v_and_b32_e32 v114, 0xffff0000, v114
	v_and_b32_e32 v115, 0xffff0000, v115
	v_and_b32_e32 v125, 0xffff0000, v116
	v_and_b32_e32 v127, 0xffff0000, v117
	v_lshlrev_b32_e32 v124, 16, v116
	v_lshlrev_b32_e32 v126, 16, v117
	v_cvt_pk_bf16_f32 v116, v118, v119
	v_cvt_pk_bf16_f32 v117, v120, v121
	v_cvt_pk_bf16_f32 v118, v156, v157
	v_cvt_pk_bf16_f32 v119, v154, v155
	v_mul_f32_e32 v114, v114, v114
	v_mul_f32_e32 v115, v115, v115
	v_mul_f32_e32 v120, v125, v125
	v_mul_f32_e32 v121, v127, v127
	v_and_b32_e32 v127, 0xffff0000, v116
	v_and_b32_e32 v129, 0xffff0000, v117
	v_and_b32_e32 v155, 0xffff0000, v118
	v_and_b32_e32 v157, 0xffff0000, v119
	v_lshlrev_b32_e32 v125, 16, v116
	v_lshlrev_b32_e32 v128, 16, v117
	v_lshlrev_b32_e32 v154, 16, v118
	v_lshlrev_b32_e32 v156, 16, v119
	v_fmac_f32_e32 v114, v122, v122
	v_fmac_f32_e32 v115, v123, v123
	v_fmac_f32_e32 v120, v124, v124
	v_fmac_f32_e32 v121, v126, v126
	v_mul_f32_e32 v122, v127, v127
	v_mul_f32_e32 v123, v129, v129
	v_mul_f32_e32 v124, v155, v155
	v_mul_f32_e32 v126, v157, v157
	v_add_f32_e32 v114, v114, v115
	v_add_f32_e32 v115, v120, v121
	v_fmac_f32_e32 v122, v125, v125
	v_fmac_f32_e32 v123, v128, v128
	v_fmac_f32_e32 v124, v154, v154
	v_fmac_f32_e32 v126, v156, v156
	v_add_f32_e32 v114, v114, v115
	v_add_f32_e32 v115, v122, v123
	v_add_f32_e32 v120, v124, v126
	v_add_f32_e32 v115, v115, v120
	v_add_f32_e32 v114, v114, v115
	ds_bpermute_b32 v115, v153, v114
	v_cndmask_b32_e32 v120, v195, v204, vcc
	v_lshlrev_b32_e32 v124, 2, v120
	global_store_dwordx4 v[148:149], v[116:119], off offset:256
	s_waitcnt lgkmcnt(0)
	v_add_f32_e32 v114, v114, v115
	ds_bpermute_b32 v115, v124, v114
	v_lshlrev_b64 v[116:117], 7, v[174:175]
	v_lshl_add_u64 v[122:123], s[10:11], 0, v[116:117]
	s_and_saveexec_b64 s[24:25], s[6:7]
	s_cbranch_execz .LBB0_1029
	v_lshl_add_u64 v[116:117], s[22:23], 2, v[122:123]
	s_lshl_b32 s96, s43, 2
	v_lshl_add_u64 v[116:117], v[116:117], 0, s[96:97]
	s_waitcnt lgkmcnt(0)
	v_add_f32_e32 v114, v114, v115
	global_store_dword v[116:117], v114, off
;     __device__ __forceinline__ void operator()(const f32x4 (&acc)[2][2][4][2], const pg8::Unit& u, int wr, int wc, int fr_, int fq_, int tid) {
;     ...
;         for (int g = 0; g < 8; ++g) {
;             const int ai = g >> 2, m = g & 3;
;             if (g < 7) ER_LD(nxt, g + 1);
;             const size_t off = base + (size_t)(ai * 128 + m * 16) * DM; float s = 0.f;
; #pragma unroll
;             for (int bj = 0; bj < 2; ++bj) {
;                 const f32x4 n0 = cur[2 * bj] + acc[ai][bj][m][0] * alpha, n1 = cur[2 * bj + 1] + acc[ai][bj][m][1] * alpha;
;                 const u32x4 w = pack8bf(n0, n1);
;                 *(u32x4*)(xb + off + bj * 128) = w;
;                 float q[8]; unpack8(w, q);
;                 s += ((q[0] * q[0] + q[1] * q[1]) + (q[2] * q[2] + q[3] * q[3])) + ((q[4] * q[4] + q[5] * q[5]) + (q[6] * q[6] + q[7] * q[7]));
;             }
;             s += __shfl_xor(s, 16); s += __shfl_xor(s, 32);
;             if (fq == 0) ssq[(size_t)(row0 + ai * 128 + m * 16) * 32 + u.pn * 4 + wc] = s;
; #pragma unroll
;             for (int j = 0; j < 4; ++j) cur[j] = nxt[j];
.LBB0_1029:
	s_or_b64 exec, exec, s[24:25]
	v_add_co_u32_e32 v114, vcc, s89, v148
	s_mov_b64 s[24:25], 0x10000
	s_waitcnt lgkmcnt(0)
	v_addc_co_u32_e32 v115, vcc, 0, v149, vcc
	global_load_dwordx4 v[118:121], v[114:115], off nt
	s_nop 0
	global_load_dwordx4 v[114:117], v[114:115], off offset:256 nt
	v_lshlrev_b32_e32 v128, 16, v134
	v_and_b32_e32 v129, 0xffff0000, v134
	v_lshlrev_b32_e32 v134, 16, v135
	v_and_b32_e32 v135, 0xffff0000, v135
	v_lshlrev_b32_e32 v154, 16, v136
	v_and_b32_e32 v155, 0xffff0000, v136
	v_lshlrev_b32_e32 v136, 16, v137
	v_and_b32_e32 v137, 0xffff0000, v137
	v_lshl_add_u64 v[126:127], v[148:149], 0, s[24:25]
	v_pk_add_f32 v[112:113], v[112:113], v[134:135]
	v_pk_add_f32 v[110:111], v[110:111], v[128:129]
	v_pk_add_f32 v[128:129], v[108:109], v[136:137]
	v_pk_add_f32 v[108:109], v[106:107], v[154:155]
	v_cvt_pk_bf16_f32 v106, v110, v111
	v_cvt_pk_bf16_f32 v107, v112, v113
	v_lshlrev_b32_e32 v156, 16, v130
	v_cvt_pk_bf16_f32 v108, v108, v109
	v_cvt_pk_bf16_f32 v109, v128, v129
	global_store_dwordx4 v[126:127], v[106:109], off
	v_lshlrev_b32_e32 v110, 16, v106
	v_lshlrev_b32_e32 v111, 16, v107
	v_and_b32_e32 v106, 0xffff0000, v106
	v_and_b32_e32 v107, 0xffff0000, v107
	v_mul_f32_e32 v106, v106, v106
	v_mul_f32_e32 v107, v107, v107
	v_lshlrev_b32_e32 v112, 16, v108
	v_and_b32_e32 v108, 0xffff0000, v108
	v_lshlrev_b32_e32 v113, 16, v109
	v_and_b32_e32 v109, 0xffff0000, v109
	v_fmac_f32_e32 v106, v110, v110
	v_fmac_f32_e32 v107, v111, v111
	v_add_f32_e32 v106, v106, v107
	v_mul_f32_e32 v107, v108, v108
	v_mul_f32_e32 v108, v109, v109
	v_and_b32_e32 v157, 0xffff0000, v130
	v_lshlrev_b32_e32 v158, 16, v132
	v_and_b32_e32 v159, 0xffff0000, v132
	v_fmac_f32_e32 v107, v112, v112
	v_fmac_f32_e32 v108, v113, v113
	v_lshlrev_b32_e32 v130, 16, v131
	v_and_b32_e32 v131, 0xffff0000, v131
	v_lshlrev_b32_e32 v132, 16, v133
	v_and_b32_e32 v133, 0xffff0000, v133
	v_add_f32_e32 v107, v107, v108
	v_pk_add_f32 v[102:103], v[102:103], v[156:157]
	v_pk_add_f32 v[98:99], v[98:99], v[158:159]
	v_add_f32_e32 v108, v106, v107
	v_pk_add_f32 v[104:105], v[104:105], v[130:131]
	v_pk_add_f32 v[106:107], v[100:101], v[132:133]
	v_cvt_pk_bf16_f32 v100, v102, v103
	v_cvt_pk_bf16_f32 v101, v104, v105
	v_cvt_pk_bf16_f32 v102, v98, v99
	s_mov_b64 s[24:25], 0x10100
	v_and_b32_e32 v99, 0xffff0000, v100
	v_lshlrev_b32_e32 v98, 16, v100
	v_and_b32_e32 v105, 0xffff0000, v101
	v_mul_f32_e32 v99, v99, v99
	v_lshlrev_b32_e32 v104, 16, v101
	v_fmac_f32_e32 v99, v98, v98
	v_mul_f32_e32 v98, v105, v105
	v_cvt_pk_bf16_f32 v103, v106, v107
	v_and_b32_e32 v107, 0xffff0000, v102
	v_and_b32_e32 v110, 0xffff0000, v103
	v_fmac_f32_e32 v98, v104, v104
	v_lshlrev_b32_e32 v106, 16, v102
	v_lshlrev_b32_e32 v109, 16, v103
	v_add_f32_e32 v98, v99, v98
	v_mul_f32_e32 v99, v107, v107
	v_mul_f32_e32 v104, v110, v110
	v_fmac_f32_e32 v99, v106, v106
	v_fmac_f32_e32 v104, v109, v109
	v_add_f32_e32 v99, v99, v104
	v_add_f32_e32 v98, v98, v99
	v_add_f32_e32 v98, v108, v98
	ds_bpermute_b32 v99, v153, v98
	v_lshl_add_u64 v[104:105], v[148:149], 0, s[24:25]
	global_store_dwordx4 v[104:105], v[100:103], off
	s_waitcnt lgkmcnt(0)
	v_add_f32_e32 v98, v98, v99
	ds_bpermute_b32 v99, v124, v98
	s_and_saveexec_b64 s[24:25], s[6:7]
	s_cbranch_execz .LBB0_1031
	s_waitcnt lgkmcnt(0)
	v_add_f32_e32 v100, v98, v99
	v_lshl_add_u64 v[98:99], s[22:23], 2, v[122:123]
	s_lshl_b32 s96, s43, 2
	v_lshl_add_u64 v[98:99], v[98:99], 0, s[96:97]
	global_store_dword v[98:99], v100, off offset:2048
.LBB0_1031:
	s_or_b64 exec, exec, s[24:25]
	v_add_co_u32_e32 v98, vcc, s90, v148
	s_waitcnt vmcnt(3)
	v_lshlrev_b32_e32 v108, 16, v118
	s_waitcnt lgkmcnt(0)
	v_addc_co_u32_e32 v99, vcc, 0, v149, vcc
	global_load_dwordx4 v[102:105], v[98:99], off nt
	s_nop 0
	global_load_dwordx4 v[98:101], v[98:99], off offset:256 nt
	v_and_b32_e32 v109, 0xffff0000, v118
	v_lshlrev_b32_e32 v110, 16, v119
	v_and_b32_e32 v111, 0xffff0000, v119
	v_lshlrev_b32_e32 v112, 16, v120
	v_and_b32_e32 v113, 0xffff0000, v120
	v_lshlrev_b32_e32 v118, 16, v121
	v_and_b32_e32 v119, 0xffff0000, v121
	v_lshl_add_u64 v[106:107], v[148:149], 0, s[64:65]
	v_pk_add_f32 v[96:97], v[96:97], v[110:111]
	v_pk_add_f32 v[94:95], v[94:95], v[108:109]
	v_pk_add_f32 v[108:109], v[92:93], v[118:119]
	v_pk_add_f32 v[92:93], v[90:91], v[112:113]
	v_cvt_pk_bf16_f32 v90, v94, v95
	v_cvt_pk_bf16_f32 v91, v96, v97
	s_waitcnt vmcnt(4)
	v_lshlrev_b32_e32 v120, 16, v114
	v_cvt_pk_bf16_f32 v92, v92, v93
	v_cvt_pk_bf16_f32 v93, v108, v109
	global_store_dwordx4 v[106:107], v[90:93], off
	v_lshlrev_b32_e32 v94, 16, v90
	v_lshlrev_b32_e32 v95, 16, v91
	v_and_b32_e32 v90, 0xffff0000, v90
	v_and_b32_e32 v91, 0xffff0000, v91
	v_mul_f32_e32 v90, v90, v90
	v_mul_f32_e32 v91, v91, v91
	v_lshlrev_b32_e32 v96, 16, v92
	v_and_b32_e32 v92, 0xffff0000, v92
	v_lshlrev_b32_e32 v97, 16, v93
	v_and_b32_e32 v93, 0xffff0000, v93
	v_fmac_f32_e32 v90, v94, v94
	v_fmac_f32_e32 v91, v95, v95
	v_add_f32_e32 v90, v90, v91
	v_mul_f32_e32 v91, v92, v92
	v_mul_f32_e32 v92, v93, v93
	v_and_b32_e32 v121, 0xffff0000, v114
	v_lshlrev_b32_e32 v126, 16, v116
	v_and_b32_e32 v127, 0xffff0000, v116
	v_fmac_f32_e32 v91, v96, v96
	v_fmac_f32_e32 v92, v97, v97
	v_lshlrev_b32_e32 v114, 16, v115
	v_and_b32_e32 v115, 0xffff0000, v115
	v_lshlrev_b32_e32 v116, 16, v117
	v_and_b32_e32 v117, 0xffff0000, v117
	v_add_f32_e32 v91, v91, v92
	v_pk_add_f32 v[86:87], v[86:87], v[120:121]
	v_pk_add_f32 v[82:83], v[82:83], v[126:127]
	v_add_f32_e32 v92, v90, v91
	v_pk_add_f32 v[88:89], v[88:89], v[114:115]
	v_pk_add_f32 v[90:91], v[84:85], v[116:117]
	v_cvt_pk_bf16_f32 v84, v86, v87
	v_cvt_pk_bf16_f32 v85, v88, v89
	v_cvt_pk_bf16_f32 v86, v82, v83
	s_mov_b64 s[24:25], 0x20100
	v_and_b32_e32 v83, 0xffff0000, v84
	v_lshlrev_b32_e32 v82, 16, v84
	v_and_b32_e32 v89, 0xffff0000, v85
	v_mul_f32_e32 v83, v83, v83
	v_lshlrev_b32_e32 v88, 16, v85
	v_fmac_f32_e32 v83, v82, v82
	v_mul_f32_e32 v82, v89, v89
	v_cvt_pk_bf16_f32 v87, v90, v91
	v_and_b32_e32 v91, 0xffff0000, v86
	v_and_b32_e32 v94, 0xffff0000, v87
	v_fmac_f32_e32 v82, v88, v88
	v_lshlrev_b32_e32 v90, 16, v86
	v_lshlrev_b32_e32 v93, 16, v87
	v_add_f32_e32 v82, v83, v82
	v_mul_f32_e32 v83, v91, v91
	v_mul_f32_e32 v88, v94, v94
	v_fmac_f32_e32 v83, v90, v90
	v_fmac_f32_e32 v88, v93, v93
	v_add_f32_e32 v83, v83, v88
	v_add_f32_e32 v82, v82, v83
	v_add_f32_e32 v82, v92, v82
	ds_bpermute_b32 v83, v153, v82
	v_lshl_add_u64 v[88:89], v[148:149], 0, s[24:25]
	global_store_dwordx4 v[88:89], v[84:87], off
	s_waitcnt lgkmcnt(0)
	v_add_f32_e32 v82, v82, v83
	ds_bpermute_b32 v83, v124, v82
	s_and_saveexec_b64 s[24:25], s[6:7]
	s_cbranch_execz .LBB0_1033
	s_waitcnt lgkmcnt(0)
	v_add_f32_e32 v84, v82, v83
	v_lshl_add_u64 v[82:83], s[22:23], 2, v[122:123]
	s_lshl_b32 s96, s43, 2
	v_lshl_add_u64 v[82:83], v[82:83], 0, s[96:97]
	v_add_co_u32_e32 v82, vcc, 0x1000, v82
	s_nop 1
	v_addc_co_u32_e32 v83, vcc, 0, v83, vcc
	global_store_dword v[82:83], v84, off
;     __device__ __forceinline__ void operator()(const f32x4 (&acc)[2][2][4][2], const pg8::Unit& u, int wr, int wc, int fr_, int fq_, int tid) {
;     ...
;         for (int g = 0; g < 8; ++g) {
;             const int ai = g >> 2, m = g & 3;
;             if (g < 7) ER_LD(nxt, g + 1);
;             const size_t off = base + (size_t)(ai * 128 + m * 16) * DM; float s = 0.f;
; #pragma unroll
;             for (int bj = 0; bj < 2; ++bj) {
;                 const f32x4 n0 = cur[2 * bj] + acc[ai][bj][m][0] * alpha, n1 = cur[2 * bj + 1] + acc[ai][bj][m][1] * alpha;
;                 const u32x4 w = pack8bf(n0, n1);
;                 *(u32x4*)(xb + off + bj * 128) = w;
;                 float q[8]; unpack8(w, q);
;                 s += ((q[0] * q[0] + q[1] * q[1]) + (q[2] * q[2] + q[3] * q[3])) + ((q[4] * q[4] + q[5] * q[5]) + (q[6] * q[6] + q[7] * q[7]));
;             }
;             s += __shfl_xor(s, 16); s += __shfl_xor(s, 32);
;             if (fq == 0) ssq[(size_t)(row0 + ai * 128 + m * 16) * 32 + u.pn * 4 + wc] = s;
; #pragma unroll
;             for (int j = 0; j < 4; ++j) cur[j] = nxt[j];
.LBB0_1033:
	s_or_b64 exec, exec, s[24:25]
	v_add_co_u32_e32 v82, vcc, s91, v148
	s_waitcnt vmcnt(3)
	v_lshlrev_b32_e32 v92, 16, v102
	s_waitcnt lgkmcnt(0)
	v_addc_co_u32_e32 v83, vcc, 0, v149, vcc
	global_load_dwordx4 v[86:89], v[82:83], off nt
	s_nop 0
	global_load_dwordx4 v[82:85], v[82:83], off offset:256 nt
	v_and_b32_e32 v93, 0xffff0000, v102
	v_lshlrev_b32_e32 v94, 16, v103
	v_and_b32_e32 v95, 0xffff0000, v103
	v_lshlrev_b32_e32 v96, 16, v104
	v_and_b32_e32 v97, 0xffff0000, v104
	v_lshlrev_b32_e32 v102, 16, v105
	v_and_b32_e32 v103, 0xffff0000, v105
	v_lshl_add_u64 v[90:91], v[148:149], 0, s[66:67]
	v_pk_add_f32 v[80:81], v[80:81], v[94:95]
	v_pk_add_f32 v[78:79], v[78:79], v[92:93]
	v_pk_add_f32 v[92:93], v[76:77], v[102:103]
	v_pk_add_f32 v[76:77], v[74:75], v[96:97]
	v_cvt_pk_bf16_f32 v74, v78, v79
	v_cvt_pk_bf16_f32 v75, v80, v81
	s_waitcnt vmcnt(4)
	v_lshlrev_b32_e32 v104, 16, v98
	v_cvt_pk_bf16_f32 v76, v76, v77
	v_cvt_pk_bf16_f32 v77, v92, v93
	global_store_dwordx4 v[90:91], v[74:77], off
	v_lshlrev_b32_e32 v78, 16, v74
	v_lshlrev_b32_e32 v79, 16, v75
	v_and_b32_e32 v74, 0xffff0000, v74
	v_and_b32_e32 v75, 0xffff0000, v75
	v_mul_f32_e32 v74, v74, v74
	v_mul_f32_e32 v75, v75, v75
	v_lshlrev_b32_e32 v80, 16, v76
	v_and_b32_e32 v76, 0xffff0000, v76
	v_lshlrev_b32_e32 v81, 16, v77
	v_and_b32_e32 v77, 0xffff0000, v77
	v_fmac_f32_e32 v74, v78, v78
	v_fmac_f32_e32 v75, v79, v79
	v_add_f32_e32 v74, v74, v75
	v_mul_f32_e32 v75, v76, v76
	v_mul_f32_e32 v76, v77, v77
	v_and_b32_e32 v105, 0xffff0000, v98
	v_lshlrev_b32_e32 v106, 16, v100
	v_and_b32_e32 v107, 0xffff0000, v100
	v_fmac_f32_e32 v75, v80, v80
	v_fmac_f32_e32 v76, v81, v81
	v_lshlrev_b32_e32 v98, 16, v99
	v_and_b32_e32 v99, 0xffff0000, v99
	v_lshlrev_b32_e32 v100, 16, v101
	v_and_b32_e32 v101, 0xffff0000, v101
	v_add_f32_e32 v75, v75, v76
	v_pk_add_f32 v[70:71], v[70:71], v[104:105]
	v_pk_add_f32 v[66:67], v[66:67], v[106:107]
	v_add_f32_e32 v76, v74, v75
	v_pk_add_f32 v[72:73], v[72:73], v[98:99]
	v_pk_add_f32 v[74:75], v[68:69], v[100:101]
	v_cvt_pk_bf16_f32 v68, v70, v71
	v_cvt_pk_bf16_f32 v69, v72, v73
	v_cvt_pk_bf16_f32 v70, v66, v67
	s_mov_b64 s[24:25], 0x30100
	v_and_b32_e32 v67, 0xffff0000, v68
	v_lshlrev_b32_e32 v66, 16, v68
	v_and_b32_e32 v73, 0xffff0000, v69
	v_mul_f32_e32 v67, v67, v67
	v_lshlrev_b32_e32 v72, 16, v69
	v_fmac_f32_e32 v67, v66, v66
	v_mul_f32_e32 v66, v73, v73
	v_cvt_pk_bf16_f32 v71, v74, v75
	v_and_b32_e32 v75, 0xffff0000, v70
	v_and_b32_e32 v78, 0xffff0000, v71
	v_fmac_f32_e32 v66, v72, v72
	v_lshlrev_b32_e32 v74, 16, v70
	v_lshlrev_b32_e32 v77, 16, v71
	v_add_f32_e32 v66, v67, v66
	v_mul_f32_e32 v67, v75, v75
	v_mul_f32_e32 v72, v78, v78
	v_fmac_f32_e32 v67, v74, v74
	v_fmac_f32_e32 v72, v77, v77
	v_add_f32_e32 v67, v67, v72
	v_add_f32_e32 v66, v66, v67
	v_add_f32_e32 v66, v76, v66
	ds_bpermute_b32 v67, v153, v66
	v_lshl_add_u64 v[72:73], v[148:149], 0, s[24:25]
	global_store_dwordx4 v[72:73], v[68:71], off
	s_waitcnt lgkmcnt(0)
	v_add_f32_e32 v66, v66, v67
	ds_bpermute_b32 v67, v124, v66
	s_and_saveexec_b64 s[24:25], s[6:7]
	s_cbranch_execz .LBB0_1035
	s_waitcnt lgkmcnt(0)
	v_add_f32_e32 v68, v66, v67
	v_lshl_add_u64 v[66:67], s[22:23], 2, v[122:123]
	s_lshl_b32 s96, s43, 2
	v_lshl_add_u64 v[66:67], v[66:67], 0, s[96:97]
	v_add_co_u32_e32 v66, vcc, 0x1000, v66
	s_nop 1
	v_addc_co_u32_e32 v67, vcc, 0, v67, vcc
	global_store_dword v[66:67], v68, off offset:2048
.LBB0_1035:
	s_or_b64 exec, exec, s[24:25]
	v_add_co_u32_e32 v66, vcc, s92, v148
	s_waitcnt vmcnt(3)
	v_lshlrev_b32_e32 v76, 16, v86
	s_waitcnt lgkmcnt(0)
	v_addc_co_u32_e32 v67, vcc, 0, v149, vcc
	global_load_dwordx4 v[70:73], v[66:67], off nt
	s_nop 0
	global_load_dwordx4 v[66:69], v[66:67], off offset:256 nt
	v_and_b32_e32 v77, 0xffff0000, v86
	v_lshlrev_b32_e32 v78, 16, v87
	v_and_b32_e32 v79, 0xffff0000, v87
	v_lshlrev_b32_e32 v80, 16, v88
	v_and_b32_e32 v81, 0xffff0000, v88
	v_lshlrev_b32_e32 v86, 16, v89
	v_and_b32_e32 v87, 0xffff0000, v89
	v_lshl_add_u64 v[74:75], v[148:149], 0, s[94:95]
	v_pk_add_f32 v[64:65], v[64:65], v[78:79]
	v_pk_add_f32 v[62:63], v[62:63], v[76:77]
	v_pk_add_f32 v[76:77], v[60:61], v[86:87]
	v_pk_add_f32 v[60:61], v[58:59], v[80:81]
	v_cvt_pk_bf16_f32 v58, v62, v63
	v_cvt_pk_bf16_f32 v59, v64, v65
	s_waitcnt vmcnt(4)
	v_lshlrev_b32_e32 v88, 16, v82
	v_cvt_pk_bf16_f32 v60, v60, v61
	v_cvt_pk_bf16_f32 v61, v76, v77
	global_store_dwordx4 v[74:75], v[58:61], off
	v_lshlrev_b32_e32 v62, 16, v58
	v_lshlrev_b32_e32 v63, 16, v59
	v_and_b32_e32 v58, 0xffff0000, v58
	v_and_b32_e32 v59, 0xffff0000, v59
	v_mul_f32_e32 v58, v58, v58
	v_mul_f32_e32 v59, v59, v59
	v_lshlrev_b32_e32 v64, 16, v60
	v_and_b32_e32 v60, 0xffff0000, v60
	v_lshlrev_b32_e32 v65, 16, v61
	v_and_b32_e32 v61, 0xffff0000, v61
	v_fmac_f32_e32 v58, v62, v62
	v_fmac_f32_e32 v59, v63, v63
	v_add_f32_e32 v58, v58, v59
	v_mul_f32_e32 v59, v60, v60
	v_mul_f32_e32 v60, v61, v61
	v_and_b32_e32 v89, 0xffff0000, v82
	v_lshlrev_b32_e32 v90, 16, v84
	v_and_b32_e32 v91, 0xffff0000, v84
	v_fmac_f32_e32 v59, v64, v64
	v_fmac_f32_e32 v60, v65, v65
	v_lshlrev_b32_e32 v82, 16, v83
	v_and_b32_e32 v83, 0xffff0000, v83
	v_lshlrev_b32_e32 v84, 16, v85
	v_and_b32_e32 v85, 0xffff0000, v85
	v_add_f32_e32 v59, v59, v60
	v_pk_add_f32 v[54:55], v[54:55], v[88:89]
	v_pk_add_f32 v[50:51], v[50:51], v[90:91]
	v_add_f32_e32 v60, v58, v59
	v_pk_add_f32 v[56:57], v[56:57], v[82:83]
	v_pk_add_f32 v[58:59], v[52:53], v[84:85]
	v_cvt_pk_bf16_f32 v52, v54, v55
	v_cvt_pk_bf16_f32 v53, v56, v57
	v_cvt_pk_bf16_f32 v54, v50, v51
	s_mov_b64 s[24:25], 0x80100
	v_and_b32_e32 v51, 0xffff0000, v52
	v_lshlrev_b32_e32 v50, 16, v52
	v_and_b32_e32 v57, 0xffff0000, v53
	v_mul_f32_e32 v51, v51, v51
	v_lshlrev_b32_e32 v56, 16, v53
	v_fmac_f32_e32 v51, v50, v50
	v_mul_f32_e32 v50, v57, v57
	v_cvt_pk_bf16_f32 v55, v58, v59
	v_and_b32_e32 v59, 0xffff0000, v54
	v_and_b32_e32 v62, 0xffff0000, v55
	v_fmac_f32_e32 v50, v56, v56
	v_lshlrev_b32_e32 v58, 16, v54
	v_lshlrev_b32_e32 v61, 16, v55
	v_add_f32_e32 v50, v51, v50
	v_mul_f32_e32 v51, v59, v59
	v_mul_f32_e32 v56, v62, v62
	v_fmac_f32_e32 v51, v58, v58
	v_fmac_f32_e32 v56, v61, v61
	v_add_f32_e32 v51, v51, v56
	v_add_f32_e32 v50, v50, v51
	v_add_f32_e32 v50, v60, v50
	ds_bpermute_b32 v51, v153, v50
	v_lshl_add_u64 v[56:57], v[148:149], 0, s[24:25]
	global_store_dwordx4 v[56:57], v[52:55], off
	s_waitcnt lgkmcnt(0)
	v_add_f32_e32 v50, v50, v51
	ds_bpermute_b32 v51, v124, v50
	s_and_saveexec_b64 s[24:25], s[6:7]
	s_cbranch_execz .LBB0_1037
	s_waitcnt lgkmcnt(0)
	v_add_f32_e32 v52, v50, v51
	v_lshl_add_u64 v[50:51], s[22:23], 2, v[122:123]
	s_lshl_b32 s96, s43, 2
	v_lshl_add_u64 v[50:51], v[50:51], 0, s[96:97]
	v_add_co_u32_e32 v50, vcc, 0x4000, v50
	s_nop 1
	v_addc_co_u32_e32 v51, vcc, 0, v51, vcc
	global_store_dword v[50:51], v52, off
;     __device__ __forceinline__ void operator()(const f32x4 (&acc)[2][2][4][2], const pg8::Unit& u, int wr, int wc, int fr_, int fq_, int tid) {
;     ...
;         for (int g = 0; g < 8; ++g) {
;             const int ai = g >> 2, m = g & 3;
;             if (g < 7) ER_LD(nxt, g + 1);
;             const size_t off = base + (size_t)(ai * 128 + m * 16) * DM; float s = 0.f;
; #pragma unroll
;             for (int bj = 0; bj < 2; ++bj) {
;                 const f32x4 n0 = cur[2 * bj] + acc[ai][bj][m][0] * alpha, n1 = cur[2 * bj + 1] + acc[ai][bj][m][1] * alpha;
;                 const u32x4 w = pack8bf(n0, n1);
;                 *(u32x4*)(xb + off + bj * 128) = w;
;                 float q[8]; unpack8(w, q);
;                 s += ((q[0] * q[0] + q[1] * q[1]) + (q[2] * q[2] + q[3] * q[3])) + ((q[4] * q[4] + q[5] * q[5]) + (q[6] * q[6] + q[7] * q[7]));
;             }
;             s += __shfl_xor(s, 16); s += __shfl_xor(s, 32);
;             if (fq == 0) ssq[(size_t)(row0 + ai * 128 + m * 16) * 32 + u.pn * 4 + wc] = s;
; #pragma unroll
;             for (int j = 0; j < 4; ++j) cur[j] = nxt[j];
.LBB0_1037:
	s_or_b64 exec, exec, s[24:25]
	v_add_co_u32_e32 v50, vcc, s59, v148
	s_waitcnt vmcnt(3)
	v_lshlrev_b32_e32 v60, 16, v70
	s_waitcnt lgkmcnt(0)
	v_addc_co_u32_e32 v51, vcc, 0, v149, vcc
	global_load_dwordx4 v[54:57], v[50:51], off nt
	s_nop 0
	global_load_dwordx4 v[50:53], v[50:51], off offset:256 nt
	v_and_b32_e32 v61, 0xffff0000, v70
	v_lshlrev_b32_e32 v62, 16, v71
	v_and_b32_e32 v63, 0xffff0000, v71
	v_lshlrev_b32_e32 v64, 16, v72
	v_and_b32_e32 v65, 0xffff0000, v72
	v_lshlrev_b32_e32 v70, 16, v73
	v_and_b32_e32 v71, 0xffff0000, v73
	v_lshl_add_u64 v[58:59], v[148:149], 0, s[68:69]
	v_pk_add_f32 v[48:49], v[48:49], v[62:63]
	v_pk_add_f32 v[46:47], v[46:47], v[60:61]
	v_pk_add_f32 v[60:61], v[44:45], v[70:71]
	v_pk_add_f32 v[44:45], v[42:43], v[64:65]
	v_cvt_pk_bf16_f32 v42, v46, v47
	v_cvt_pk_bf16_f32 v43, v48, v49
	s_waitcnt vmcnt(4)
	v_lshlrev_b32_e32 v72, 16, v66
	v_cvt_pk_bf16_f32 v44, v44, v45
	v_cvt_pk_bf16_f32 v45, v60, v61
	global_store_dwordx4 v[58:59], v[42:45], off
	v_lshlrev_b32_e32 v46, 16, v42
	v_lshlrev_b32_e32 v47, 16, v43
	v_and_b32_e32 v42, 0xffff0000, v42
	v_and_b32_e32 v43, 0xffff0000, v43
	v_mul_f32_e32 v42, v42, v42
	v_mul_f32_e32 v43, v43, v43
	v_lshlrev_b32_e32 v48, 16, v44
	v_and_b32_e32 v44, 0xffff0000, v44
	v_lshlrev_b32_e32 v49, 16, v45
	v_and_b32_e32 v45, 0xffff0000, v45
	v_fmac_f32_e32 v42, v46, v46
	v_fmac_f32_e32 v43, v47, v47
	v_add_f32_e32 v42, v42, v43
	v_mul_f32_e32 v43, v44, v44
	v_mul_f32_e32 v44, v45, v45
	v_and_b32_e32 v73, 0xffff0000, v66
	v_lshlrev_b32_e32 v74, 16, v68
	v_and_b32_e32 v75, 0xffff0000, v68
	v_fmac_f32_e32 v43, v48, v48
	v_fmac_f32_e32 v44, v49, v49
	v_lshlrev_b32_e32 v66, 16, v67
	v_and_b32_e32 v67, 0xffff0000, v67
	v_lshlrev_b32_e32 v68, 16, v69
	v_and_b32_e32 v69, 0xffff0000, v69
	v_add_f32_e32 v43, v43, v44
	v_pk_add_f32 v[38:39], v[38:39], v[72:73]
	v_pk_add_f32 v[34:35], v[34:35], v[74:75]
	v_add_f32_e32 v44, v42, v43
	v_pk_add_f32 v[40:41], v[40:41], v[66:67]
	v_pk_add_f32 v[42:43], v[36:37], v[68:69]
	v_cvt_pk_bf16_f32 v36, v38, v39
	v_cvt_pk_bf16_f32 v37, v40, v41
	v_cvt_pk_bf16_f32 v38, v34, v35
	s_mov_b64 s[24:25], 0x90100
	v_and_b32_e32 v35, 0xffff0000, v36
	v_lshlrev_b32_e32 v34, 16, v36
	v_and_b32_e32 v41, 0xffff0000, v37
	v_mul_f32_e32 v35, v35, v35
	v_lshlrev_b32_e32 v40, 16, v37
	v_fmac_f32_e32 v35, v34, v34
	v_mul_f32_e32 v34, v41, v41
	v_cvt_pk_bf16_f32 v39, v42, v43
	v_and_b32_e32 v43, 0xffff0000, v38
	v_and_b32_e32 v46, 0xffff0000, v39
	v_fmac_f32_e32 v34, v40, v40
	v_lshlrev_b32_e32 v42, 16, v38
	v_lshlrev_b32_e32 v45, 16, v39
	v_add_f32_e32 v34, v35, v34
	v_mul_f32_e32 v35, v43, v43
	v_mul_f32_e32 v40, v46, v46
	v_fmac_f32_e32 v35, v42, v42
	v_fmac_f32_e32 v40, v45, v45
	v_add_f32_e32 v35, v35, v40
	v_add_f32_e32 v34, v34, v35
	v_add_f32_e32 v34, v44, v34
	ds_bpermute_b32 v35, v153, v34
	v_lshl_add_u64 v[40:41], v[148:149], 0, s[24:25]
	global_store_dwordx4 v[40:41], v[36:39], off
	s_waitcnt lgkmcnt(0)
	v_add_f32_e32 v34, v34, v35
	ds_bpermute_b32 v35, v124, v34
	s_and_saveexec_b64 s[24:25], s[6:7]
	s_cbranch_execz .LBB0_1039
	s_waitcnt lgkmcnt(0)
	v_add_f32_e32 v36, v34, v35
	v_lshl_add_u64 v[34:35], s[22:23], 2, v[122:123]
	s_lshl_b32 s96, s43, 2
	v_lshl_add_u64 v[34:35], v[34:35], 0, s[96:97]
	v_add_co_u32_e32 v34, vcc, 0x4000, v34
	s_nop 1
	v_addc_co_u32_e32 v35, vcc, 0, v35, vcc
	global_store_dword v[34:35], v36, off offset:2048
.LBB0_1039:
	s_or_b64 exec, exec, s[24:25]
	v_add_co_u32_e32 v34, vcc, s60, v148
	s_waitcnt vmcnt(3)
	v_lshlrev_b32_e32 v44, 16, v54
	s_waitcnt lgkmcnt(0)
	v_addc_co_u32_e32 v35, vcc, 0, v149, vcc
	global_load_dwordx4 v[38:41], v[34:35], off nt
	s_nop 0
	global_load_dwordx4 v[34:37], v[34:35], off offset:256 nt
	v_and_b32_e32 v45, 0xffff0000, v54
	v_lshlrev_b32_e32 v46, 16, v55
	v_and_b32_e32 v47, 0xffff0000, v55
	v_lshlrev_b32_e32 v48, 16, v56
	v_and_b32_e32 v49, 0xffff0000, v56
	v_lshlrev_b32_e32 v54, 16, v57
	v_and_b32_e32 v55, 0xffff0000, v57
	v_lshl_add_u64 v[42:43], v[148:149], 0, s[70:71]
	v_pk_add_f32 v[32:33], v[32:33], v[46:47]
	v_pk_add_f32 v[30:31], v[30:31], v[44:45]
	v_pk_add_f32 v[44:45], v[28:29], v[54:55]
	v_pk_add_f32 v[28:29], v[26:27], v[48:49]
	v_cvt_pk_bf16_f32 v26, v30, v31
	v_cvt_pk_bf16_f32 v27, v32, v33
	s_waitcnt vmcnt(4)
	v_lshlrev_b32_e32 v56, 16, v50
	v_cvt_pk_bf16_f32 v28, v28, v29
	v_cvt_pk_bf16_f32 v29, v44, v45
	global_store_dwordx4 v[42:43], v[26:29], off
	v_lshlrev_b32_e32 v30, 16, v26
	v_lshlrev_b32_e32 v31, 16, v27
	v_and_b32_e32 v26, 0xffff0000, v26
	v_and_b32_e32 v27, 0xffff0000, v27
	v_mul_f32_e32 v26, v26, v26
	v_mul_f32_e32 v27, v27, v27
	v_lshlrev_b32_e32 v32, 16, v28
	v_and_b32_e32 v28, 0xffff0000, v28
	v_lshlrev_b32_e32 v33, 16, v29
	v_and_b32_e32 v29, 0xffff0000, v29
	v_fmac_f32_e32 v26, v30, v30
	v_fmac_f32_e32 v27, v31, v31
	v_add_f32_e32 v26, v26, v27
	v_mul_f32_e32 v27, v28, v28
	v_mul_f32_e32 v28, v29, v29
	v_and_b32_e32 v57, 0xffff0000, v50
	v_lshlrev_b32_e32 v58, 16, v52
	v_and_b32_e32 v59, 0xffff0000, v52
	v_fmac_f32_e32 v27, v32, v32
	v_fmac_f32_e32 v28, v33, v33
	v_lshlrev_b32_e32 v50, 16, v51
	v_and_b32_e32 v51, 0xffff0000, v51
	v_lshlrev_b32_e32 v52, 16, v53
	v_and_b32_e32 v53, 0xffff0000, v53
	v_add_f32_e32 v27, v27, v28
	v_pk_add_f32 v[22:23], v[22:23], v[56:57]
	v_pk_add_f32 v[18:19], v[18:19], v[58:59]
	v_add_f32_e32 v28, v26, v27
	v_pk_add_f32 v[24:25], v[24:25], v[50:51]
	v_pk_add_f32 v[26:27], v[20:21], v[52:53]
	v_cvt_pk_bf16_f32 v20, v22, v23
	v_cvt_pk_bf16_f32 v21, v24, v25
	v_cvt_pk_bf16_f32 v22, v18, v19
	s_mov_b64 s[24:25], 0xa0100
	v_and_b32_e32 v19, 0xffff0000, v20
	v_lshlrev_b32_e32 v18, 16, v20
	v_and_b32_e32 v25, 0xffff0000, v21
	v_mul_f32_e32 v19, v19, v19
	v_lshlrev_b32_e32 v24, 16, v21
	v_fmac_f32_e32 v19, v18, v18
	v_mul_f32_e32 v18, v25, v25
	v_cvt_pk_bf16_f32 v23, v26, v27
	v_and_b32_e32 v27, 0xffff0000, v22
	v_and_b32_e32 v30, 0xffff0000, v23
	v_fmac_f32_e32 v18, v24, v24
	v_lshlrev_b32_e32 v26, 16, v22
	v_lshlrev_b32_e32 v29, 16, v23
	v_add_f32_e32 v18, v19, v18
	v_mul_f32_e32 v19, v27, v27
	v_mul_f32_e32 v24, v30, v30
	v_fmac_f32_e32 v19, v26, v26
	v_fmac_f32_e32 v24, v29, v29
	v_add_f32_e32 v19, v19, v24
	v_add_f32_e32 v18, v18, v19
	v_add_f32_e32 v18, v28, v18
	ds_bpermute_b32 v19, v153, v18
	v_lshl_add_u64 v[24:25], v[148:149], 0, s[24:25]
	global_store_dwordx4 v[24:25], v[20:23], off
	s_waitcnt lgkmcnt(0)
	v_add_f32_e32 v18, v18, v19
	ds_bpermute_b32 v19, v124, v18
	s_and_saveexec_b64 s[24:25], s[6:7]
	s_cbranch_execz .LBB0_1041
	s_waitcnt lgkmcnt(0)
	v_add_f32_e32 v20, v18, v19
	v_lshl_add_u64 v[18:19], s[22:23], 2, v[122:123]
	s_lshl_b32 s96, s43, 2
	v_lshl_add_u64 v[18:19], v[18:19], 0, s[96:97]
	v_add_co_u32_e32 v18, vcc, 0x5000, v18
	s_nop 1
	v_addc_co_u32_e32 v19, vcc, 0, v19, vcc
	global_store_dword v[18:19], v20, off

;     __device__ __forceinline__ void operator()(const f32x4 (&acc)[2][2][4][2], const pg8::Unit& u, int wr, int wc, int fr_, int fq_, int tid) {
;     ...
;         const size_t base = (size_t)row0 * DM + col0;
;         f32x4 cur[4], nxt[4];
;     ...
;         ER_LD(cur, 0);
; #pragma unroll
;         for (int g = 0; g < 8; ++g) {
;             const int ai = g >> 2, m = g & 3;
;             if (g < 7) ER_LD(nxt, g + 1);
;             const size_t off = base + (size_t)(ai * 128 + m * 16) * DM; float s = 0.f;
; #pragma unroll
;             for (int bj = 0; bj < 2; ++bj) {
;                 const f32x4 n0 = cur[2 * bj] + acc[ai][bj][m][0] * alpha, n1 = cur[2 * bj + 1] + acc[ai][bj][m][1] * alpha;
;                 const u32x4 w = pack8bf(n0, n1);
;                 *(u32x4*)(xb + off + bj * 128) = w;
;                 float q[8]; unpack8(w, q);
;                 s += ((q[0] * q[0] + q[1] * q[1]) + (q[2] * q[2] + q[3] * q[3])) + ((q[4] * q[4] + q[5] * q[5]) + (q[6] * q[6] + q[7] * q[7]));
;             }
;             s += __shfl_xor(s, 16); s += __shfl_xor(s, 32);
;             if (fq == 0) ssq[(size_t)(row0 + ai * 128 + m * 16) * 32 + u.pn * 4 + wc] = s;
.LBB0_1227:
	s_lshl_b32 s6, s48, 8
	v_mov_b32_e32 v130, v1
	v_mov_b32_e32 v173, v150
	s_add_i32 s6, s6, s38
	v_cmp_lt_i32_e32 vcc, v203, v198
	v_add_u32_e32 v174, s6, v130
	s_lshl_b32 s6, s47, 8
	s_or_b32 s6, s6, s39
	v_ashrrev_i32_e32 v175, 31, v174
	v_lshl_add_u32 v130, v173, 3, s6
	v_lshlrev_b64 v[132:133], 12, v[174:175]
	v_ashrrev_i32_e32 v131, 31, v130
	v_lshl_add_u64 v[132:133], s[8:9], 0, v[132:133]
	v_lshl_add_u64 v[148:149], v[130:131], 1, v[132:133]
	global_load_dwordx4 v[154:157], v[148:149], off nt
	global_load_dwordx4 v[158:161], v[148:149], off offset:256 nt
	v_cndmask_b32_e32 v130, v195, v203, vcc
	v_lshlrev_b32_e32 v153, 2, v130
	v_add_co_u32_e32 v130, vcc, s86, v148
	s_lshl_b32 s18, s47, 2
	s_nop 0
	v_addc_co_u32_e32 v131, vcc, 0, v149, vcc
	global_load_dwordx4 v[134:137], v[130:131], off nt
	s_nop 0
	global_load_dwordx4 v[130:133], v[130:131], off offset:256 nt
	v_cmp_lt_i32_e32 vcc, v204, v198
	v_cmp_eq_u32_e64 s[6:7], 0, v173
	s_ashr_i32 s19, s18, 31
	s_waitcnt vmcnt(0)
	v_lshlrev_b32_e32 v176, 16, v154
	v_and_b32_e32 v177, 0xffff0000, v154
	v_lshlrev_b32_e32 v154, 16, v155
	v_and_b32_e32 v155, 0xffff0000, v155
	v_lshlrev_b32_e32 v178, 16, v156
	v_and_b32_e32 v179, 0xffff0000, v156
	v_lshlrev_b32_e32 v156, 16, v157
	v_and_b32_e32 v157, 0xffff0000, v157
	v_lshlrev_b32_e32 v182, 16, v160
	v_and_b32_e32 v183, 0xffff0000, v160
	v_lshlrev_b32_e32 v180, 16, v158
	v_and_b32_e32 v181, 0xffff0000, v158
	v_lshlrev_b32_e32 v158, 16, v159
	v_and_b32_e32 v159, 0xffff0000, v159
	v_lshlrev_b32_e32 v160, 16, v161
	v_and_b32_e32 v161, 0xffff0000, v161
	v_pk_fma_f32 v[128:129], v[128:129], 0.5, v[154:155] op_sel_hi:[1,0,1]
	v_pk_fma_f32 v[126:127], v[126:127], 0.5, v[176:177] op_sel_hi:[1,0,1]
	v_pk_fma_f32 v[124:125], v[124:125], 0.5, v[156:157] op_sel_hi:[1,0,1]
	v_pk_fma_f32 v[122:123], v[122:123], 0.5, v[178:179] op_sel_hi:[1,0,1]
	v_pk_fma_f32 v[156:157], v[114:115], 0.5, v[182:183] op_sel_hi:[1,0,1]
	v_cvt_pk_bf16_f32 v114, v126, v127
	v_cvt_pk_bf16_f32 v115, v128, v129
	v_pk_fma_f32 v[120:121], v[120:121], 0.5, v[158:159] op_sel_hi:[1,0,1]
	v_pk_fma_f32 v[118:119], v[118:119], 0.5, v[180:181] op_sel_hi:[1,0,1]
	v_pk_fma_f32 v[154:155], v[116:117], 0.5, v[160:161] op_sel_hi:[1,0,1]
	v_cvt_pk_bf16_f32 v116, v122, v123
	v_cvt_pk_bf16_f32 v117, v124, v125
	global_store_dwordx4 v[148:149], v[114:117], off
	v_lshlrev_b32_e32 v122, 16, v114
	v_lshlrev_b32_e32 v123, 16, v115
	v_and_b32_e32 v114, 0xffff0000, v114
	v_and_b32_e32 v115, 0xffff0000, v115
	v_and_b32_e32 v125, 0xffff0000, v116
	v_and_b32_e32 v127, 0xffff0000, v117
	v_lshlrev_b32_e32 v124, 16, v116
	v_lshlrev_b32_e32 v126, 16, v117
	v_cvt_pk_bf16_f32 v116, v118, v119
	v_cvt_pk_bf16_f32 v117, v120, v121
	v_cvt_pk_bf16_f32 v118, v156, v157
	v_cvt_pk_bf16_f32 v119, v154, v155
	v_mul_f32_e32 v114, v114, v114
	v_mul_f32_e32 v115, v115, v115
	v_mul_f32_e32 v120, v125, v125
	v_mul_f32_e32 v121, v127, v127
	v_and_b32_e32 v127, 0xffff0000, v116
	v_and_b32_e32 v129, 0xffff0000, v117
	v_and_b32_e32 v155, 0xffff0000, v118
	v_and_b32_e32 v157, 0xffff0000, v119
	v_lshlrev_b32_e32 v125, 16, v116
	v_lshlrev_b32_e32 v128, 16, v117
	v_lshlrev_b32_e32 v154, 16, v118
	v_lshlrev_b32_e32 v156, 16, v119
	v_fmac_f32_e32 v114, v122, v122
	v_fmac_f32_e32 v115, v123, v123
	v_fmac_f32_e32 v120, v124, v124
	v_fmac_f32_e32 v121, v126, v126
	v_mul_f32_e32 v122, v127, v127
	v_mul_f32_e32 v123, v129, v129
	v_mul_f32_e32 v124, v155, v155
	v_mul_f32_e32 v126, v157, v157
	v_add_f32_e32 v114, v114, v115
	v_add_f32_e32 v115, v120, v121
	v_fmac_f32_e32 v122, v125, v125
	v_fmac_f32_e32 v123, v128, v128
	v_fmac_f32_e32 v124, v154, v154
	v_fmac_f32_e32 v126, v156, v156
	v_add_f32_e32 v114, v114, v115
	v_add_f32_e32 v115, v122, v123
	v_add_f32_e32 v120, v124, v126
	v_add_f32_e32 v115, v115, v120
	v_add_f32_e32 v114, v114, v115
	ds_bpermute_b32 v115, v153, v114
	v_cndmask_b32_e32 v120, v195, v204, vcc
	v_lshlrev_b32_e32 v124, 2, v120
	global_store_dwordx4 v[148:149], v[116:119], off offset:256
	s_waitcnt lgkmcnt(0)
	v_add_f32_e32 v114, v114, v115
	ds_bpermute_b32 v115, v124, v114
	v_lshlrev_b64 v[116:117], 7, v[174:175]
	v_lshl_add_u64 v[122:123], s[10:11], 0, v[116:117]
	s_and_saveexec_b64 s[20:21], s[6:7]
	s_cbranch_execz .LBB0_1229
	v_lshl_add_u64 v[116:117], s[18:19], 2, v[122:123]
	s_lshl_b32 s96, s37, 2
	v_lshl_add_u64 v[116:117], v[116:117], 0, s[96:97]
	s_waitcnt lgkmcnt(0)
	v_add_f32_e32 v114, v114, v115
	global_store_dword v[116:117], v114, off
;     __device__ __forceinline__ void operator()(const f32x4 (&acc)[2][2][4][2], const pg8::Unit& u, int wr, int wc, int fr_, int fq_, int tid) {
;     ...
;         for (int g = 0; g < 8; ++g) {
;             const int ai = g >> 2, m = g & 3;
;             if (g < 7) ER_LD(nxt, g + 1);
;             const size_t off = base + (size_t)(ai * 128 + m * 16) * DM; float s = 0.f;
; #pragma unroll
;             for (int bj = 0; bj < 2; ++bj) {
;                 const f32x4 n0 = cur[2 * bj] + acc[ai][bj][m][0] * alpha, n1 = cur[2 * bj + 1] + acc[ai][bj][m][1] * alpha;
;                 const u32x4 w = pack8bf(n0, n1);
;                 *(u32x4*)(xb + off + bj * 128) = w;
;                 float q[8]; unpack8(w, q);
;                 s += ((q[0] * q[0] + q[1] * q[1]) + (q[2] * q[2] + q[3] * q[3])) + ((q[4] * q[4] + q[5] * q[5]) + (q[6] * q[6] + q[7] * q[7]));
;             }
;             s += __shfl_xor(s, 16); s += __shfl_xor(s, 32);
;             if (fq == 0) ssq[(size_t)(row0 + ai * 128 + m * 16) * 32 + u.pn * 4 + wc] = s;
; #pragma unroll
;             for (int j = 0; j < 4; ++j) cur[j] = nxt[j];
.LBB0_1229:
	s_or_b64 exec, exec, s[20:21]
	v_add_co_u32_e32 v114, vcc, s89, v148
	s_mov_b64 s[20:21], 0x10000
	s_waitcnt lgkmcnt(0)
	v_addc_co_u32_e32 v115, vcc, 0, v149, vcc
	global_load_dwordx4 v[118:121], v[114:115], off nt
	s_nop 0
	global_load_dwordx4 v[114:117], v[114:115], off offset:256 nt
	v_lshlrev_b32_e32 v128, 16, v134
	v_and_b32_e32 v129, 0xffff0000, v134
	v_lshlrev_b32_e32 v134, 16, v135
	v_and_b32_e32 v135, 0xffff0000, v135
	v_lshlrev_b32_e32 v154, 16, v136
	v_and_b32_e32 v155, 0xffff0000, v136
	v_lshlrev_b32_e32 v136, 16, v137
	v_and_b32_e32 v137, 0xffff0000, v137
	v_lshl_add_u64 v[126:127], v[148:149], 0, s[20:21]
	v_pk_fma_f32 v[112:113], v[112:113], 0.5, v[134:135] op_sel_hi:[1,0,1]
	v_pk_fma_f32 v[110:111], v[110:111], 0.5, v[128:129] op_sel_hi:[1,0,1]
	v_pk_fma_f32 v[128:129], v[108:109], 0.5, v[136:137] op_sel_hi:[1,0,1]
	v_pk_fma_f32 v[108:109], v[106:107], 0.5, v[154:155] op_sel_hi:[1,0,1]
	v_cvt_pk_bf16_f32 v106, v110, v111
	v_cvt_pk_bf16_f32 v107, v112, v113
	v_lshlrev_b32_e32 v156, 16, v130
	v_cvt_pk_bf16_f32 v108, v108, v109
	v_cvt_pk_bf16_f32 v109, v128, v129
	global_store_dwordx4 v[126:127], v[106:109], off
	v_lshlrev_b32_e32 v110, 16, v106
	v_lshlrev_b32_e32 v111, 16, v107
	v_and_b32_e32 v106, 0xffff0000, v106
	v_and_b32_e32 v107, 0xffff0000, v107
	v_mul_f32_e32 v106, v106, v106
	v_mul_f32_e32 v107, v107, v107
	v_lshlrev_b32_e32 v112, 16, v108
	v_and_b32_e32 v108, 0xffff0000, v108
	v_lshlrev_b32_e32 v113, 16, v109
	v_and_b32_e32 v109, 0xffff0000, v109
	v_fmac_f32_e32 v106, v110, v110
	v_fmac_f32_e32 v107, v111, v111
	v_add_f32_e32 v106, v106, v107
	v_mul_f32_e32 v107, v108, v108
	v_mul_f32_e32 v108, v109, v109
	v_and_b32_e32 v157, 0xffff0000, v130
	v_lshlrev_b32_e32 v158, 16, v132
	v_and_b32_e32 v159, 0xffff0000, v132
	v_fmac_f32_e32 v107, v112, v112
	v_fmac_f32_e32 v108, v113, v113
	v_lshlrev_b32_e32 v130, 16, v131
	v_and_b32_e32 v131, 0xffff0000, v131
	v_lshlrev_b32_e32 v132, 16, v133
	v_and_b32_e32 v133, 0xffff0000, v133
	v_add_f32_e32 v107, v107, v108
	v_pk_fma_f32 v[102:103], v[102:103], 0.5, v[156:157] op_sel_hi:[1,0,1]
	v_pk_fma_f32 v[98:99], v[98:99], 0.5, v[158:159] op_sel_hi:[1,0,1]
	v_add_f32_e32 v108, v106, v107
	v_pk_fma_f32 v[104:105], v[104:105], 0.5, v[130:131] op_sel_hi:[1,0,1]
	v_pk_fma_f32 v[106:107], v[100:101], 0.5, v[132:133] op_sel_hi:[1,0,1]
	v_cvt_pk_bf16_f32 v100, v102, v103
	v_cvt_pk_bf16_f32 v101, v104, v105
	v_cvt_pk_bf16_f32 v102, v98, v99
	s_mov_b64 s[20:21], 0x10100
	v_and_b32_e32 v99, 0xffff0000, v100
	v_lshlrev_b32_e32 v98, 16, v100
	v_and_b32_e32 v105, 0xffff0000, v101
	v_mul_f32_e32 v99, v99, v99
	v_lshlrev_b32_e32 v104, 16, v101
	v_fmac_f32_e32 v99, v98, v98
	v_mul_f32_e32 v98, v105, v105
	v_cvt_pk_bf16_f32 v103, v106, v107
	v_and_b32_e32 v107, 0xffff0000, v102
	v_and_b32_e32 v110, 0xffff0000, v103
	v_fmac_f32_e32 v98, v104, v104
	v_lshlrev_b32_e32 v106, 16, v102
	v_lshlrev_b32_e32 v109, 16, v103
	v_add_f32_e32 v98, v99, v98
	v_mul_f32_e32 v99, v107, v107
	v_mul_f32_e32 v104, v110, v110
	v_fmac_f32_e32 v99, v106, v106
	v_fmac_f32_e32 v104, v109, v109
	v_add_f32_e32 v99, v99, v104
	v_add_f32_e32 v98, v98, v99
	v_add_f32_e32 v98, v108, v98
	ds_bpermute_b32 v99, v153, v98
	v_lshl_add_u64 v[104:105], v[148:149], 0, s[20:21]
	global_store_dwordx4 v[104:105], v[100:103], off
	s_waitcnt lgkmcnt(0)
	v_add_f32_e32 v98, v98, v99
	ds_bpermute_b32 v99, v124, v98
	s_and_saveexec_b64 s[20:21], s[6:7]
	s_cbranch_execz .LBB0_1231
	s_waitcnt lgkmcnt(0)
	v_add_f32_e32 v100, v98, v99
	v_lshl_add_u64 v[98:99], s[18:19], 2, v[122:123]
	s_lshl_b32 s96, s37, 2
	v_lshl_add_u64 v[98:99], v[98:99], 0, s[96:97]
	global_store_dword v[98:99], v100, off offset:2048
.LBB0_1231:
	s_or_b64 exec, exec, s[20:21]
	v_add_co_u32_e32 v98, vcc, s90, v148
	s_waitcnt vmcnt(3)
	v_lshlrev_b32_e32 v108, 16, v118
	s_waitcnt lgkmcnt(0)
	v_addc_co_u32_e32 v99, vcc, 0, v149, vcc
	global_load_dwordx4 v[102:105], v[98:99], off nt
	s_nop 0
	global_load_dwordx4 v[98:101], v[98:99], off offset:256 nt
	v_and_b32_e32 v109, 0xffff0000, v118
	v_lshlrev_b32_e32 v110, 16, v119
	v_and_b32_e32 v111, 0xffff0000, v119
	v_lshlrev_b32_e32 v112, 16, v120
	v_and_b32_e32 v113, 0xffff0000, v120
	v_lshlrev_b32_e32 v118, 16, v121
	v_and_b32_e32 v119, 0xffff0000, v121
	v_lshl_add_u64 v[106:107], v[148:149], 0, s[64:65]
	v_pk_fma_f32 v[96:97], v[96:97], 0.5, v[110:111] op_sel_hi:[1,0,1]
	v_pk_fma_f32 v[94:95], v[94:95], 0.5, v[108:109] op_sel_hi:[1,0,1]
	v_pk_fma_f32 v[108:109], v[92:93], 0.5, v[118:119] op_sel_hi:[1,0,1]
	v_pk_fma_f32 v[92:93], v[90:91], 0.5, v[112:113] op_sel_hi:[1,0,1]
	v_cvt_pk_bf16_f32 v90, v94, v95
	v_cvt_pk_bf16_f32 v91, v96, v97
	s_waitcnt vmcnt(4)
	v_lshlrev_b32_e32 v120, 16, v114
	v_cvt_pk_bf16_f32 v92, v92, v93
	v_cvt_pk_bf16_f32 v93, v108, v109
	global_store_dwordx4 v[106:107], v[90:93], off
	v_lshlrev_b32_e32 v94, 16, v90
	v_lshlrev_b32_e32 v95, 16, v91
	v_and_b32_e32 v90, 0xffff0000, v90
	v_and_b32_e32 v91, 0xffff0000, v91
	v_mul_f32_e32 v90, v90, v90
	v_mul_f32_e32 v91, v91, v91
	v_lshlrev_b32_e32 v96, 16, v92
	v_and_b32_e32 v92, 0xffff0000, v92
	v_lshlrev_b32_e32 v97, 16, v93
	v_and_b32_e32 v93, 0xffff0000, v93
	v_fmac_f32_e32 v90, v94, v94
	v_fmac_f32_e32 v91, v95, v95
	v_add_f32_e32 v90, v90, v91
	v_mul_f32_e32 v91, v92, v92
	v_mul_f32_e32 v92, v93, v93
	v_and_b32_e32 v121, 0xffff0000, v114
	v_lshlrev_b32_e32 v126, 16, v116
	v_and_b32_e32 v127, 0xffff0000, v116
	v_fmac_f32_e32 v91, v96, v96
	v_fmac_f32_e32 v92, v97, v97
	v_lshlrev_b32_e32 v114, 16, v115
	v_and_b32_e32 v115, 0xffff0000, v115
	v_lshlrev_b32_e32 v116, 16, v117
	v_and_b32_e32 v117, 0xffff0000, v117
	v_add_f32_e32 v91, v91, v92
	v_pk_fma_f32 v[86:87], v[86:87], 0.5, v[120:121] op_sel_hi:[1,0,1]
	v_pk_fma_f32 v[82:83], v[82:83], 0.5, v[126:127] op_sel_hi:[1,0,1]
	v_add_f32_e32 v92, v90, v91
	v_pk_fma_f32 v[88:89], v[88:89], 0.5, v[114:115] op_sel_hi:[1,0,1]
	v_pk_fma_f32 v[90:91], v[84:85], 0.5, v[116:117] op_sel_hi:[1,0,1]
	v_cvt_pk_bf16_f32 v84, v86, v87
	v_cvt_pk_bf16_f32 v85, v88, v89
	v_cvt_pk_bf16_f32 v86, v82, v83
	s_mov_b64 s[20:21], 0x20100
	v_and_b32_e32 v83, 0xffff0000, v84
	v_lshlrev_b32_e32 v82, 16, v84
	v_and_b32_e32 v89, 0xffff0000, v85
	v_mul_f32_e32 v83, v83, v83
	v_lshlrev_b32_e32 v88, 16, v85
	v_fmac_f32_e32 v83, v82, v82
	v_mul_f32_e32 v82, v89, v89
	v_cvt_pk_bf16_f32 v87, v90, v91
	v_and_b32_e32 v91, 0xffff0000, v86
	v_and_b32_e32 v94, 0xffff0000, v87
	v_fmac_f32_e32 v82, v88, v88
	v_lshlrev_b32_e32 v90, 16, v86
	v_lshlrev_b32_e32 v93, 16, v87
	v_add_f32_e32 v82, v83, v82
	v_mul_f32_e32 v83, v91, v91
	v_mul_f32_e32 v88, v94, v94
	v_fmac_f32_e32 v83, v90, v90
	v_fmac_f32_e32 v88, v93, v93
	v_add_f32_e32 v83, v83, v88
	v_add_f32_e32 v82, v82, v83
	v_add_f32_e32 v82, v92, v82
	ds_bpermute_b32 v83, v153, v82
	v_lshl_add_u64 v[88:89], v[148:149], 0, s[20:21]
	global_store_dwordx4 v[88:89], v[84:87], off
	s_waitcnt lgkmcnt(0)
	v_add_f32_e32 v82, v82, v83
	ds_bpermute_b32 v83, v124, v82
	s_and_saveexec_b64 s[20:21], s[6:7]
	s_cbranch_execz .LBB0_1233
;     __device__ __forceinline__ void operator()(const f32x4 (&acc)[2][2][4][2], const pg8::Unit& u, int wr, int wc, int fr_, int fq_, int tid) {
;     ...
;         for (int g = 0; g < 8; ++g) {
;             const int ai = g >> 2, m = g & 3;
;             if (g < 7) ER_LD(nxt, g + 1);
;             const size_t off = base + (size_t)(ai * 128 + m * 16) * DM; float s = 0.f;
; #pragma unroll
;             for (int bj = 0; bj < 2; ++bj) {
;                 const f32x4 n0 = cur[2 * bj] + acc[ai][bj][m][0] * alpha, n1 = cur[2 * bj + 1] + acc[ai][bj][m][1] * alpha;
;                 const u32x4 w = pack8bf(n0, n1);
;                 *(u32x4*)(xb + off + bj * 128) = w;
;                 float q[8]; unpack8(w, q);
;                 s += ((q[0] * q[0] + q[1] * q[1]) + (q[2] * q[2] + q[3] * q[3])) + ((q[4] * q[4] + q[5] * q[5]) + (q[6] * q[6] + q[7] * q[7]));
;             }
;             s += __shfl_xor(s, 16); s += __shfl_xor(s, 32);
;             if (fq == 0) ssq[(size_t)(row0 + ai * 128 + m * 16) * 32 + u.pn * 4 + wc] = s;
; #pragma unroll
;             for (int j = 0; j < 4; ++j) cur[j] = nxt[j];
	s_waitcnt lgkmcnt(0)
	v_add_f32_e32 v84, v82, v83
	v_lshl_add_u64 v[82:83], s[18:19], 2, v[122:123]
	s_lshl_b32 s96, s37, 2
	v_lshl_add_u64 v[82:83], v[82:83], 0, s[96:97]
	v_add_co_u32_e32 v82, vcc, 0x1000, v82
	s_nop 1
	v_addc_co_u32_e32 v83, vcc, 0, v83, vcc
	global_store_dword v[82:83], v84, off
.LBB0_1233:
	s_or_b64 exec, exec, s[20:21]
	v_add_co_u32_e32 v82, vcc, s91, v148
	s_waitcnt vmcnt(3)
	v_lshlrev_b32_e32 v92, 16, v102
	s_waitcnt lgkmcnt(0)
	v_addc_co_u32_e32 v83, vcc, 0, v149, vcc
	global_load_dwordx4 v[86:89], v[82:83], off nt
	s_nop 0
	global_load_dwordx4 v[82:85], v[82:83], off offset:256 nt
	v_and_b32_e32 v93, 0xffff0000, v102
	v_lshlrev_b32_e32 v94, 16, v103
	v_and_b32_e32 v95, 0xffff0000, v103
	v_lshlrev_b32_e32 v96, 16, v104
	v_and_b32_e32 v97, 0xffff0000, v104
	v_lshlrev_b32_e32 v102, 16, v105
	v_and_b32_e32 v103, 0xffff0000, v105
	v_lshl_add_u64 v[90:91], v[148:149], 0, s[66:67]
	v_pk_fma_f32 v[80:81], v[80:81], 0.5, v[94:95] op_sel_hi:[1,0,1]
	v_pk_fma_f32 v[78:79], v[78:79], 0.5, v[92:93] op_sel_hi:[1,0,1]
	v_pk_fma_f32 v[92:93], v[76:77], 0.5, v[102:103] op_sel_hi:[1,0,1]
	v_pk_fma_f32 v[76:77], v[74:75], 0.5, v[96:97] op_sel_hi:[1,0,1]
	v_cvt_pk_bf16_f32 v74, v78, v79
	v_cvt_pk_bf16_f32 v75, v80, v81
	s_waitcnt vmcnt(4)
	v_lshlrev_b32_e32 v104, 16, v98
	v_cvt_pk_bf16_f32 v76, v76, v77
	v_cvt_pk_bf16_f32 v77, v92, v93
	global_store_dwordx4 v[90:91], v[74:77], off
	v_lshlrev_b32_e32 v78, 16, v74
	v_lshlrev_b32_e32 v79, 16, v75
	v_and_b32_e32 v74, 0xffff0000, v74
	v_and_b32_e32 v75, 0xffff0000, v75
	v_mul_f32_e32 v74, v74, v74
	v_mul_f32_e32 v75, v75, v75
	v_lshlrev_b32_e32 v80, 16, v76
	v_and_b32_e32 v76, 0xffff0000, v76
	v_lshlrev_b32_e32 v81, 16, v77
	v_and_b32_e32 v77, 0xffff0000, v77
	v_fmac_f32_e32 v74, v78, v78
	v_fmac_f32_e32 v75, v79, v79
	v_add_f32_e32 v74, v74, v75
	v_mul_f32_e32 v75, v76, v76
	v_mul_f32_e32 v76, v77, v77
	v_and_b32_e32 v105, 0xffff0000, v98
	v_lshlrev_b32_e32 v106, 16, v100
	v_and_b32_e32 v107, 0xffff0000, v100
	v_fmac_f32_e32 v75, v80, v80
	v_fmac_f32_e32 v76, v81, v81
	v_lshlrev_b32_e32 v98, 16, v99
	v_and_b32_e32 v99, 0xffff0000, v99
	v_lshlrev_b32_e32 v100, 16, v101
	v_and_b32_e32 v101, 0xffff0000, v101
	v_add_f32_e32 v75, v75, v76
	v_pk_fma_f32 v[70:71], v[70:71], 0.5, v[104:105] op_sel_hi:[1,0,1]
	v_pk_fma_f32 v[66:67], v[66:67], 0.5, v[106:107] op_sel_hi:[1,0,1]
	v_add_f32_e32 v76, v74, v75
	v_pk_fma_f32 v[72:73], v[72:73], 0.5, v[98:99] op_sel_hi:[1,0,1]
	v_pk_fma_f32 v[74:75], v[68:69], 0.5, v[100:101] op_sel_hi:[1,0,1]
	v_cvt_pk_bf16_f32 v68, v70, v71
	v_cvt_pk_bf16_f32 v69, v72, v73
	v_cvt_pk_bf16_f32 v70, v66, v67
	s_mov_b64 s[20:21], 0x30100
	v_and_b32_e32 v67, 0xffff0000, v68
	v_lshlrev_b32_e32 v66, 16, v68
	v_and_b32_e32 v73, 0xffff0000, v69
	v_mul_f32_e32 v67, v67, v67
	v_lshlrev_b32_e32 v72, 16, v69
	v_fmac_f32_e32 v67, v66, v66
	v_mul_f32_e32 v66, v73, v73
	v_cvt_pk_bf16_f32 v71, v74, v75
	v_and_b32_e32 v75, 0xffff0000, v70
	v_and_b32_e32 v78, 0xffff0000, v71
	v_fmac_f32_e32 v66, v72, v72
	v_lshlrev_b32_e32 v74, 16, v70
	v_lshlrev_b32_e32 v77, 16, v71
	v_add_f32_e32 v66, v67, v66
	v_mul_f32_e32 v67, v75, v75
	v_mul_f32_e32 v72, v78, v78
	v_fmac_f32_e32 v67, v74, v74
	v_fmac_f32_e32 v72, v77, v77
	v_add_f32_e32 v67, v67, v72
	v_add_f32_e32 v66, v66, v67
	v_add_f32_e32 v66, v76, v66
	ds_bpermute_b32 v67, v153, v66
	v_lshl_add_u64 v[72:73], v[148:149], 0, s[20:21]
	global_store_dwordx4 v[72:73], v[68:71], off
	s_waitcnt lgkmcnt(0)
	v_add_f32_e32 v66, v66, v67
	ds_bpermute_b32 v67, v124, v66
	s_and_saveexec_b64 s[20:21], s[6:7]
	s_cbranch_execz .LBB0_1235
	s_waitcnt lgkmcnt(0)
	v_add_f32_e32 v68, v66, v67
	v_lshl_add_u64 v[66:67], s[18:19], 2, v[122:123]
	s_lshl_b32 s96, s37, 2
	v_lshl_add_u64 v[66:67], v[66:67], 0, s[96:97]
	v_add_co_u32_e32 v66, vcc, 0x1000, v66
	s_nop 1
	v_addc_co_u32_e32 v67, vcc, 0, v67, vcc
	global_store_dword v[66:67], v68, off offset:2048
.LBB0_1235:
	s_or_b64 exec, exec, s[20:21]
	v_add_co_u32_e32 v66, vcc, s92, v148
	s_waitcnt vmcnt(3)
	v_lshlrev_b32_e32 v76, 16, v86
	s_waitcnt lgkmcnt(0)
	v_addc_co_u32_e32 v67, vcc, 0, v149, vcc
	global_load_dwordx4 v[70:73], v[66:67], off nt
	s_nop 0
	global_load_dwordx4 v[66:69], v[66:67], off offset:256 nt
	v_and_b32_e32 v77, 0xffff0000, v86
	v_lshlrev_b32_e32 v78, 16, v87
	v_and_b32_e32 v79, 0xffff0000, v87
	v_lshlrev_b32_e32 v80, 16, v88
	v_and_b32_e32 v81, 0xffff0000, v88
	v_lshlrev_b32_e32 v86, 16, v89
	v_and_b32_e32 v87, 0xffff0000, v89
	v_lshl_add_u64 v[74:75], v[148:149], 0, s[94:95]
	v_pk_fma_f32 v[64:65], v[64:65], 0.5, v[78:79] op_sel_hi:[1,0,1]
	v_pk_fma_f32 v[62:63], v[62:63], 0.5, v[76:77] op_sel_hi:[1,0,1]
	v_pk_fma_f32 v[76:77], v[60:61], 0.5, v[86:87] op_sel_hi:[1,0,1]
	v_pk_fma_f32 v[60:61], v[58:59], 0.5, v[80:81] op_sel_hi:[1,0,1]
	v_cvt_pk_bf16_f32 v58, v62, v63
	v_cvt_pk_bf16_f32 v59, v64, v65
	s_waitcnt vmcnt(4)
;     __device__ __forceinline__ void operator()(const f32x4 (&acc)[2][2][4][2], const pg8::Unit& u, int wr, int wc, int fr_, int fq_, int tid) {
;     ...
;         for (int g = 0; g < 8; ++g) {
;             const int ai = g >> 2, m = g & 3;
;             if (g < 7) ER_LD(nxt, g + 1);
;             const size_t off = base + (size_t)(ai * 128 + m * 16) * DM; float s = 0.f;
; #pragma unroll
;             for (int bj = 0; bj < 2; ++bj) {
;                 const f32x4 n0 = cur[2 * bj] + acc[ai][bj][m][0] * alpha, n1 = cur[2 * bj + 1] + acc[ai][bj][m][1] * alpha;
;                 const u32x4 w = pack8bf(n0, n1);
;                 *(u32x4*)(xb + off + bj * 128) = w;
;                 float q[8]; unpack8(w, q);
;                 s += ((q[0] * q[0] + q[1] * q[1]) + (q[2] * q[2] + q[3] * q[3])) + ((q[4] * q[4] + q[5] * q[5]) + (q[6] * q[6] + q[7] * q[7]));
;             }
;             s += __shfl_xor(s, 16); s += __shfl_xor(s, 32);
;             if (fq == 0) ssq[(size_t)(row0 + ai * 128 + m * 16) * 32 + u.pn * 4 + wc] = s;
; #pragma unroll
;             for (int j = 0; j < 4; ++j) cur[j] = nxt[j];
	v_lshlrev_b32_e32 v88, 16, v82
	v_cvt_pk_bf16_f32 v60, v60, v61
	v_cvt_pk_bf16_f32 v61, v76, v77
	global_store_dwordx4 v[74:75], v[58:61], off
	v_lshlrev_b32_e32 v62, 16, v58
	v_lshlrev_b32_e32 v63, 16, v59
	v_and_b32_e32 v58, 0xffff0000, v58
	v_and_b32_e32 v59, 0xffff0000, v59
	v_mul_f32_e32 v58, v58, v58
	v_mul_f32_e32 v59, v59, v59
	v_lshlrev_b32_e32 v64, 16, v60
	v_and_b32_e32 v60, 0xffff0000, v60
	v_lshlrev_b32_e32 v65, 16, v61
	v_and_b32_e32 v61, 0xffff0000, v61
	v_fmac_f32_e32 v58, v62, v62
	v_fmac_f32_e32 v59, v63, v63
	v_add_f32_e32 v58, v58, v59
	v_mul_f32_e32 v59, v60, v60
	v_mul_f32_e32 v60, v61, v61
	v_and_b32_e32 v89, 0xffff0000, v82
	v_lshlrev_b32_e32 v90, 16, v84
	v_and_b32_e32 v91, 0xffff0000, v84
	v_fmac_f32_e32 v59, v64, v64
	v_fmac_f32_e32 v60, v65, v65
	v_lshlrev_b32_e32 v82, 16, v83
	v_and_b32_e32 v83, 0xffff0000, v83
	v_lshlrev_b32_e32 v84, 16, v85
	v_and_b32_e32 v85, 0xffff0000, v85
	v_add_f32_e32 v59, v59, v60
	v_pk_fma_f32 v[54:55], v[54:55], 0.5, v[88:89] op_sel_hi:[1,0,1]
	v_pk_fma_f32 v[50:51], v[50:51], 0.5, v[90:91] op_sel_hi:[1,0,1]
	v_add_f32_e32 v60, v58, v59
	v_pk_fma_f32 v[56:57], v[56:57], 0.5, v[82:83] op_sel_hi:[1,0,1]
	v_pk_fma_f32 v[58:59], v[52:53], 0.5, v[84:85] op_sel_hi:[1,0,1]
	v_cvt_pk_bf16_f32 v52, v54, v55
	v_cvt_pk_bf16_f32 v53, v56, v57
	v_cvt_pk_bf16_f32 v54, v50, v51
	s_mov_b64 s[20:21], 0x80100
	v_and_b32_e32 v51, 0xffff0000, v52
	v_lshlrev_b32_e32 v50, 16, v52
	v_and_b32_e32 v57, 0xffff0000, v53
	v_mul_f32_e32 v51, v51, v51
	v_lshlrev_b32_e32 v56, 16, v53
	v_fmac_f32_e32 v51, v50, v50
	v_mul_f32_e32 v50, v57, v57
	v_cvt_pk_bf16_f32 v55, v58, v59
	v_and_b32_e32 v59, 0xffff0000, v54
	v_and_b32_e32 v62, 0xffff0000, v55
	v_fmac_f32_e32 v50, v56, v56
	v_lshlrev_b32_e32 v58, 16, v54
	v_lshlrev_b32_e32 v61, 16, v55
	v_add_f32_e32 v50, v51, v50
	v_mul_f32_e32 v51, v59, v59
	v_mul_f32_e32 v56, v62, v62
	v_fmac_f32_e32 v51, v58, v58
	v_fmac_f32_e32 v56, v61, v61
	v_add_f32_e32 v51, v51, v56
	v_add_f32_e32 v50, v50, v51
	v_add_f32_e32 v50, v60, v50
	ds_bpermute_b32 v51, v153, v50
	v_lshl_add_u64 v[56:57], v[148:149], 0, s[20:21]
	global_store_dwordx4 v[56:57], v[52:55], off
	s_waitcnt lgkmcnt(0)
	v_add_f32_e32 v50, v50, v51
	ds_bpermute_b32 v51, v124, v50
	s_and_saveexec_b64 s[20:21], s[6:7]
	s_cbranch_execz .LBB0_1237
	s_waitcnt lgkmcnt(0)
	v_add_f32_e32 v52, v50, v51
	v_lshl_add_u64 v[50:51], s[18:19], 2, v[122:123]
	s_lshl_b32 s96, s37, 2
	v_lshl_add_u64 v[50:51], v[50:51], 0, s[96:97]
	v_add_co_u32_e32 v50, vcc, 0x4000, v50
	s_nop 1
	v_addc_co_u32_e32 v51, vcc, 0, v51, vcc
	global_store_dword v[50:51], v52, off
.LBB0_1237:
	s_or_b64 exec, exec, s[20:21]
	v_add_co_u32_e32 v50, vcc, s59, v148
	s_waitcnt vmcnt(3)
	v_lshlrev_b32_e32 v60, 16, v70
	s_waitcnt lgkmcnt(0)
	v_addc_co_u32_e32 v51, vcc, 0, v149, vcc
	global_load_dwordx4 v[54:57], v[50:51], off nt
	s_nop 0
	global_load_dwordx4 v[50:53], v[50:51], off offset:256 nt
	v_and_b32_e32 v61, 0xffff0000, v70
	v_lshlrev_b32_e32 v62, 16, v71
	v_and_b32_e32 v63, 0xffff0000, v71
	v_lshlrev_b32_e32 v64, 16, v72
	v_and_b32_e32 v65, 0xffff0000, v72
	v_lshlrev_b32_e32 v70, 16, v73
	v_and_b32_e32 v71, 0xffff0000, v73
	v_lshl_add_u64 v[58:59], v[148:149], 0, s[68:69]
	v_pk_fma_f32 v[48:49], v[48:49], 0.5, v[62:63] op_sel_hi:[1,0,1]
	v_pk_fma_f32 v[46:47], v[46:47], 0.5, v[60:61] op_sel_hi:[1,0,1]
	v_pk_fma_f32 v[60:61], v[44:45], 0.5, v[70:71] op_sel_hi:[1,0,1]
	v_pk_fma_f32 v[44:45], v[42:43], 0.5, v[64:65] op_sel_hi:[1,0,1]
	v_cvt_pk_bf16_f32 v42, v46, v47
	v_cvt_pk_bf16_f32 v43, v48, v49
	s_waitcnt vmcnt(4)
	v_lshlrev_b32_e32 v72, 16, v66
	v_cvt_pk_bf16_f32 v44, v44, v45
	v_cvt_pk_bf16_f32 v45, v60, v61
	global_store_dwordx4 v[58:59], v[42:45], off
	v_lshlrev_b32_e32 v46, 16, v42
	v_lshlrev_b32_e32 v47, 16, v43
	v_and_b32_e32 v42, 0xffff0000, v42
	v_and_b32_e32 v43, 0xffff0000, v43
	v_mul_f32_e32 v42, v42, v42
	v_mul_f32_e32 v43, v43, v43
	v_lshlrev_b32_e32 v48, 16, v44
	v_and_b32_e32 v44, 0xffff0000, v44
	v_lshlrev_b32_e32 v49, 16, v45
	v_and_b32_e32 v45, 0xffff0000, v45
	v_fmac_f32_e32 v42, v46, v46
	v_fmac_f32_e32 v43, v47, v47
	v_add_f32_e32 v42, v42, v43
	v_mul_f32_e32 v43, v44, v44
	v_mul_f32_e32 v44, v45, v45
	v_and_b32_e32 v73, 0xffff0000, v66
	v_lshlrev_b32_e32 v74, 16, v68
	v_and_b32_e32 v75, 0xffff0000, v68
	v_fmac_f32_e32 v43, v48, v48
	v_fmac_f32_e32 v44, v49, v49
	v_lshlrev_b32_e32 v66, 16, v67
	v_and_b32_e32 v67, 0xffff0000, v67
	v_lshlrev_b32_e32 v68, 16, v69
	v_and_b32_e32 v69, 0xffff0000, v69
	v_add_f32_e32 v43, v43, v44
	v_pk_fma_f32 v[38:39], v[38:39], 0.5, v[72:73] op_sel_hi:[1,0,1]
	v_pk_fma_f32 v[34:35], v[34:35], 0.5, v[74:75] op_sel_hi:[1,0,1]
	v_add_f32_e32 v44, v42, v43
	v_pk_fma_f32 v[40:41], v[40:41], 0.5, v[66:67] op_sel_hi:[1,0,1]
	v_pk_fma_f32 v[42:43], v[36:37], 0.5, v[68:69] op_sel_hi:[1,0,1]
	v_cvt_pk_bf16_f32 v36, v38, v39
	v_cvt_pk_bf16_f32 v37, v40, v41
	v_cvt_pk_bf16_f32 v38, v34, v35
	s_mov_b64 s[20:21], 0x90100
	v_and_b32_e32 v35, 0xffff0000, v36
	v_lshlrev_b32_e32 v34, 16, v36
	v_and_b32_e32 v41, 0xffff0000, v37
	v_mul_f32_e32 v35, v35, v35
	v_lshlrev_b32_e32 v40, 16, v37
	v_fmac_f32_e32 v35, v34, v34
	v_mul_f32_e32 v34, v41, v41
	v_cvt_pk_bf16_f32 v39, v42, v43
	v_and_b32_e32 v43, 0xffff0000, v38
	v_and_b32_e32 v46, 0xffff0000, v39
	v_fmac_f32_e32 v34, v40, v40
	v_lshlrev_b32_e32 v42, 16, v38
	v_lshlrev_b32_e32 v45, 16, v39
	v_add_f32_e32 v34, v35, v34
	v_mul_f32_e32 v35, v43, v43
	v_mul_f32_e32 v40, v46, v46
	v_fmac_f32_e32 v35, v42, v42
	v_fmac_f32_e32 v40, v45, v45
	v_add_f32_e32 v35, v35, v40
	v_add_f32_e32 v34, v34, v35
	v_add_f32_e32 v34, v44, v34
	ds_bpermute_b32 v35, v153, v34
	v_lshl_add_u64 v[40:41], v[148:149], 0, s[20:21]
	global_store_dwordx4 v[40:41], v[36:39], off
	s_waitcnt lgkmcnt(0)
	v_add_f32_e32 v34, v34, v35
	ds_bpermute_b32 v35, v124, v34
	s_and_saveexec_b64 s[20:21], s[6:7]
	s_cbranch_execz .LBB0_1239
	s_waitcnt lgkmcnt(0)
	v_add_f32_e32 v36, v34, v35
	v_lshl_add_u64 v[34:35], s[18:19], 2, v[122:123]
	s_lshl_b32 s96, s37, 2
	v_lshl_add_u64 v[34:35], v[34:35], 0, s[96:97]
	v_add_co_u32_e32 v34, vcc, 0x4000, v34
	s_nop 1
	v_addc_co_u32_e32 v35, vcc, 0, v35, vcc
	global_store_dword v[34:35], v36, off offset:2048
;     __device__ __forceinline__ void operator()(const f32x4 (&acc)[2][2][4][2], const pg8::Unit& u, int wr, int wc, int fr_, int fq_, int tid) {
;     ...
;         for (int g = 0; g < 8; ++g) {
;             const int ai = g >> 2, m = g & 3;
;             if (g < 7) ER_LD(nxt, g + 1);
;             const size_t off = base + (size_t)(ai * 128 + m * 16) * DM; float s = 0.f;
; #pragma unroll
;             for (int bj = 0; bj < 2; ++bj) {
;                 const f32x4 n0 = cur[2 * bj] + acc[ai][bj][m][0] * alpha, n1 = cur[2 * bj + 1] + acc[ai][bj][m][1] * alpha;
;                 const u32x4 w = pack8bf(n0, n1);
;                 *(u32x4*)(xb + off + bj * 128) = w;
;                 float q[8]; unpack8(w, q);
;                 s += ((q[0] * q[0] + q[1] * q[1]) + (q[2] * q[2] + q[3] * q[3])) + ((q[4] * q[4] + q[5] * q[5]) + (q[6] * q[6] + q[7] * q[7]));
;             }
;             s += __shfl_xor(s, 16); s += __shfl_xor(s, 32);
;             if (fq == 0) ssq[(size_t)(row0 + ai * 128 + m * 16) * 32 + u.pn * 4 + wc] = s;
; #pragma unroll
;             for (int j = 0; j < 4; ++j) cur[j] = nxt[j];
.LBB0_1239:
	s_or_b64 exec, exec, s[20:21]
	v_add_co_u32_e32 v34, vcc, s60, v148
	s_waitcnt vmcnt(3)
	v_lshlrev_b32_e32 v44, 16, v54
	s_waitcnt lgkmcnt(0)
	v_addc_co_u32_e32 v35, vcc, 0, v149, vcc
	global_load_dwordx4 v[38:41], v[34:35], off nt
	s_nop 0
	global_load_dwordx4 v[34:37], v[34:35], off offset:256 nt
	v_and_b32_e32 v45, 0xffff0000, v54
	v_lshlrev_b32_e32 v46, 16, v55
	v_and_b32_e32 v47, 0xffff0000, v55
	v_lshlrev_b32_e32 v48, 16, v56
	v_and_b32_e32 v49, 0xffff0000, v56
	v_lshlrev_b32_e32 v54, 16, v57
	v_and_b32_e32 v55, 0xffff0000, v57
	v_lshl_add_u64 v[42:43], v[148:149], 0, s[70:71]
	v_pk_fma_f32 v[32:33], v[32:33], 0.5, v[46:47] op_sel_hi:[1,0,1]
	v_pk_fma_f32 v[30:31], v[30:31], 0.5, v[44:45] op_sel_hi:[1,0,1]
	v_pk_fma_f32 v[44:45], v[28:29], 0.5, v[54:55] op_sel_hi:[1,0,1]
	v_pk_fma_f32 v[28:29], v[26:27], 0.5, v[48:49] op_sel_hi:[1,0,1]
	v_cvt_pk_bf16_f32 v26, v30, v31
	v_cvt_pk_bf16_f32 v27, v32, v33
	s_waitcnt vmcnt(4)
	v_lshlrev_b32_e32 v56, 16, v50
	v_cvt_pk_bf16_f32 v28, v28, v29
	v_cvt_pk_bf16_f32 v29, v44, v45
	global_store_dwordx4 v[42:43], v[26:29], off
	v_lshlrev_b32_e32 v30, 16, v26
	v_lshlrev_b32_e32 v31, 16, v27
	v_and_b32_e32 v26, 0xffff0000, v26
	v_and_b32_e32 v27, 0xffff0000, v27
	v_mul_f32_e32 v26, v26, v26
	v_mul_f32_e32 v27, v27, v27
	v_lshlrev_b32_e32 v32, 16, v28
	v_and_b32_e32 v28, 0xffff0000, v28
	v_lshlrev_b32_e32 v33, 16, v29
	v_and_b32_e32 v29, 0xffff0000, v29
	v_fmac_f32_e32 v26, v30, v30
	v_fmac_f32_e32 v27, v31, v31
	v_add_f32_e32 v26, v26, v27
	v_mul_f32_e32 v27, v28, v28
	v_mul_f32_e32 v28, v29, v29
	v_and_b32_e32 v57, 0xffff0000, v50
	v_lshlrev_b32_e32 v58, 16, v52
	v_and_b32_e32 v59, 0xffff0000, v52
	v_fmac_f32_e32 v27, v32, v32
	v_fmac_f32_e32 v28, v33, v33
	v_lshlrev_b32_e32 v50, 16, v51
	v_and_b32_e32 v51, 0xffff0000, v51
	v_lshlrev_b32_e32 v52, 16, v53
	v_and_b32_e32 v53, 0xffff0000, v53
	v_add_f32_e32 v27, v27, v28
	v_pk_fma_f32 v[22:23], v[22:23], 0.5, v[56:57] op_sel_hi:[1,0,1]
	v_pk_fma_f32 v[18:19], v[18:19], 0.5, v[58:59] op_sel_hi:[1,0,1]
	v_add_f32_e32 v28, v26, v27
	v_pk_fma_f32 v[24:25], v[24:25], 0.5, v[50:51] op_sel_hi:[1,0,1]
	v_pk_fma_f32 v[26:27], v[20:21], 0.5, v[52:53] op_sel_hi:[1,0,1]
	v_cvt_pk_bf16_f32 v20, v22, v23
	v_cvt_pk_bf16_f32 v21, v24, v25
	v_cvt_pk_bf16_f32 v22, v18, v19
	s_mov_b64 s[20:21], 0xa0100
	v_and_b32_e32 v19, 0xffff0000, v20
	v_lshlrev_b32_e32 v18, 16, v20
	v_and_b32_e32 v25, 0xffff0000, v21
	v_mul_f32_e32 v19, v19, v19
	v_lshlrev_b32_e32 v24, 16, v21
	v_fmac_f32_e32 v19, v18, v18
	v_mul_f32_e32 v18, v25, v25
	v_cvt_pk_bf16_f32 v23, v26, v27
	v_and_b32_e32 v27, 0xffff0000, v22
	v_and_b32_e32 v30, 0xffff0000, v23
	v_fmac_f32_e32 v18, v24, v24
	v_lshlrev_b32_e32 v26, 16, v22
	v_lshlrev_b32_e32 v29, 16, v23
	v_add_f32_e32 v18, v19, v18
	v_mul_f32_e32 v19, v27, v27
	v_mul_f32_e32 v24, v30, v30
	v_fmac_f32_e32 v19, v26, v26
	v_fmac_f32_e32 v24, v29, v29
	v_add_f32_e32 v19, v19, v24
	v_add_f32_e32 v18, v18, v19
	v_add_f32_e32 v18, v28, v18
	ds_bpermute_b32 v19, v153, v18
	v_lshl_add_u64 v[24:25], v[148:149], 0, s[20:21]
	global_store_dwordx4 v[24:25], v[20:23], off
	s_waitcnt lgkmcnt(0)
	v_add_f32_e32 v18, v18, v19
	ds_bpermute_b32 v19, v124, v18
	s_and_saveexec_b64 s[20:21], s[6:7]
	s_cbranch_execz .LBB0_1241
	s_waitcnt lgkmcnt(0)
	v_add_f32_e32 v20, v18, v19
	v_lshl_add_u64 v[18:19], s[18:19], 2, v[122:123]
	s_lshl_b32 s96, s37, 2
	v_lshl_add_u64 v[18:19], v[18:19], 0, s[96:97]
	v_add_co_u32_e32 v18, vcc, 0x5000, v18
	s_nop 1
	v_addc_co_u32_e32 v19, vcc, 0, v19, vcc
	global_store_dword v[18:19], v20, off
